# W_out epilogue (P8) rewritten by hand (hoisted loads, packed fma, permlane reduction); residual-load waits in the hand-written down/W_out epilogues cover both column halves of a row group
# speedup vs baseline: 1.0047x; 1.0047x over previous
.LBB0_196:
	v_ashrrev_i32_e32 v142, 2, v192
	v_and_b32_e32 v142, 0xffffffc0, v142
	s_lshl_b32 vcc_lo, s73, 8
	v_and_or_b32 v143, v192, 15, vcc_lo
	v_add_u32_e32 v142, v143, v142
	v_ashrrev_i32_e32 v143, 31, v142
	v_bfe_u32 v147, v192, 4, 2
	v_lshrrev_b32_e32 v80, 1, v192
	v_and_b32_e32 v80, 0x60, v80
	s_lshl_b32 vcc_lo, s72, 8
	v_add_u32_e32 v80, vcc_lo, v80
	v_lshl_add_u32 v80, v147, 3, v80
	v_lshlrev_b32_e32 v80, 1, v80
	v_lshlrev_b64 v[164:165], 11, v[142:143]
	v_lshl_add_u64 v[164:165], s[38:39], 0, v[164:165]
	v_lshl_add_u64 v[164:165], v[164:165], 0, v[80:81]
	v_mov_b32_e32 v248, v164
	v_mov_b32_e32 v249, v165
	global_load_dwordx4 v[148:151], v[248:249], off
	global_load_dwordx4 v[160:163], v[248:249], off offset:256
	s_mov_b64 vcc, 0x8000
	s_nop 0
	v_lshl_add_u64 v[248:249], v[248:249], 0, vcc
	global_load_dwordx4 v[176:179], v[248:249], off
	global_load_dwordx4 v[180:183], v[248:249], off offset:256
	s_mov_b64 vcc, 0x8000
	s_nop 0
	v_lshl_add_u64 v[248:249], v[248:249], 0, vcc
	global_load_dwordx4 v[184:187], v[248:249], off
	global_load_dwordx4 v[188:191], v[248:249], off offset:256
	s_mov_b64 vcc, 0x8000
	s_nop 0
	v_lshl_add_u64 v[248:249], v[248:249], 0, vcc
	global_load_dwordx4 v[204:207], v[248:249], off
	global_load_dwordx4 v[208:211], v[248:249], off offset:256
	s_mov_b64 vcc, 0x28000
	s_nop 0
	v_lshl_add_u64 v[248:249], v[248:249], 0, vcc
	global_load_dwordx4 v[212:215], v[248:249], off
	global_load_dwordx4 v[216:219], v[248:249], off offset:256
	s_mov_b64 vcc, 0x8000
	s_nop 0
	v_lshl_add_u64 v[248:249], v[248:249], 0, vcc
	global_load_dwordx4 v[220:223], v[248:249], off
	global_load_dwordx4 v[224:227], v[248:249], off offset:256
	s_mov_b64 vcc, 0x8000
	s_nop 0
	v_lshl_add_u64 v[248:249], v[248:249], 0, vcc
	global_load_dwordx4 v[228:231], v[248:249], off
	global_load_dwordx4 v[232:235], v[248:249], off offset:256
	s_mov_b64 vcc, 0x8000
	s_nop 0
	v_lshl_add_u64 v[248:249], v[248:249], 0, vcc
	global_load_dwordx4 v[236:239], v[248:249], off
	global_load_dwordx4 v[240:243], v[248:249], off offset:256
	v_readlane_b32 s54, v253, 14
	v_readlane_b32 s55, v253, 15
	v_cmp_eq_u32_e64 s[46:47], 0, v147
	s_nop 0
	v_lshl_add_u64 v[166:167], v[142:143], 2, s[54:55]
	s_waitcnt vmcnt(14)
	v_lshlrev_b32_e32 v168, 16, v148
	v_and_b32_e32 v169, 0xffff0000, v148
	v_lshlrev_b32_e32 v170, 16, v149
	v_and_b32_e32 v171, 0xffff0000, v149
	v_lshlrev_b32_e32 v172, 16, v150
	v_and_b32_e32 v173, 0xffff0000, v150
	v_lshlrev_b32_e32 v174, 16, v151
	v_and_b32_e32 v175, 0xffff0000, v151
	v_pk_fma_f32 v[168:169], v[126:127], 0.5, v[168:169] op_sel_hi:[1,0,1]
	v_pk_fma_f32 v[170:171], v[128:129], 0.5, v[170:171] op_sel_hi:[1,0,1]
	v_pk_fma_f32 v[172:173], v[122:123], 0.5, v[172:173] op_sel_hi:[1,0,1]
	v_pk_fma_f32 v[174:175], v[124:125], 0.5, v[174:175] op_sel_hi:[1,0,1]
	v_pk_mul_f32 v[244:245], v[168:169], v[168:169]
	v_pk_fma_f32 v[244:245], v[170:171], v[170:171], v[244:245]
	v_pk_fma_f32 v[244:245], v[172:173], v[172:173], v[244:245]
	v_pk_fma_f32 v[244:245], v[174:175], v[174:175], v[244:245]
	v_cvt_pk_bf16_f32 v148, v168, v169
	v_cvt_pk_bf16_f32 v149, v170, v171
	v_cvt_pk_bf16_f32 v150, v172, v173
	v_cvt_pk_bf16_f32 v151, v174, v175
	global_store_dwordx4 v[164:165], v[148:151], off
	v_lshlrev_b32_e32 v168, 16, v160
	v_and_b32_e32 v169, 0xffff0000, v160
	v_lshlrev_b32_e32 v170, 16, v161
	v_and_b32_e32 v171, 0xffff0000, v161
	v_lshlrev_b32_e32 v172, 16, v162
	v_and_b32_e32 v173, 0xffff0000, v162
	v_lshlrev_b32_e32 v174, 16, v163
	v_and_b32_e32 v175, 0xffff0000, v163
	v_pk_fma_f32 v[168:169], v[118:119], 0.5, v[168:169] op_sel_hi:[1,0,1]
	v_pk_fma_f32 v[170:171], v[120:121], 0.5, v[170:171] op_sel_hi:[1,0,1]
	v_pk_fma_f32 v[172:173], v[114:115], 0.5, v[172:173] op_sel_hi:[1,0,1]
	v_pk_fma_f32 v[174:175], v[116:117], 0.5, v[174:175] op_sel_hi:[1,0,1]
	v_pk_fma_f32 v[244:245], v[168:169], v[168:169], v[244:245]
	v_pk_fma_f32 v[244:245], v[170:171], v[170:171], v[244:245]
	v_pk_fma_f32 v[244:245], v[172:173], v[172:173], v[244:245]
	v_pk_fma_f32 v[244:245], v[174:175], v[174:175], v[244:245]
	v_cvt_pk_bf16_f32 v160, v168, v169
	v_cvt_pk_bf16_f32 v161, v170, v171
	v_cvt_pk_bf16_f32 v162, v172, v173
	v_cvt_pk_bf16_f32 v163, v174, v175
	global_store_dwordx4 v[164:165], v[160:163], off offset:256
	v_add_f32_e32 v246, v244, v245
	v_mov_b32_e32 v247, v246
	s_nop 1
	v_permlane32_swap_b32 v247, v246
	s_nop 1
	v_add_f32_e32 v246, v246, v247
	v_mov_b32_e32 v247, v246
	s_nop 1
	v_permlane16_swap_b32 v247, v246
	s_nop 1
	v_add_f32_e32 v246, v246, v247
	s_mov_b64 exec, s[46:47]
	global_atomic_add_f32 v[166:167], v246, off
	s_mov_b64 exec, -1
	s_mov_b64 vcc, 0x8000
	s_nop 0
	v_lshl_add_u64 v[164:165], v[164:165], 0, vcc
	s_waitcnt vmcnt(15)
	v_lshlrev_b32_e32 v168, 16, v176
	v_and_b32_e32 v169, 0xffff0000, v176
	v_lshlrev_b32_e32 v170, 16, v177
	v_and_b32_e32 v171, 0xffff0000, v177
	v_lshlrev_b32_e32 v172, 16, v178
	v_and_b32_e32 v173, 0xffff0000, v178
	v_lshlrev_b32_e32 v174, 16, v179
	v_and_b32_e32 v175, 0xffff0000, v179
	v_pk_fma_f32 v[168:169], v[110:111], 0.5, v[168:169] op_sel_hi:[1,0,1]
	v_pk_fma_f32 v[170:171], v[112:113], 0.5, v[170:171] op_sel_hi:[1,0,1]
	v_pk_fma_f32 v[172:173], v[106:107], 0.5, v[172:173] op_sel_hi:[1,0,1]
	v_pk_fma_f32 v[174:175], v[108:109], 0.5, v[174:175] op_sel_hi:[1,0,1]
	v_pk_mul_f32 v[244:245], v[168:169], v[168:169]
	v_pk_fma_f32 v[244:245], v[170:171], v[170:171], v[244:245]
	v_pk_fma_f32 v[244:245], v[172:173], v[172:173], v[244:245]
	v_pk_fma_f32 v[244:245], v[174:175], v[174:175], v[244:245]
	v_cvt_pk_bf16_f32 v176, v168, v169
	v_cvt_pk_bf16_f32 v177, v170, v171
	v_cvt_pk_bf16_f32 v178, v172, v173
	v_cvt_pk_bf16_f32 v179, v174, v175
	global_store_dwordx4 v[164:165], v[176:179], off
	v_lshlrev_b32_e32 v168, 16, v180
	v_and_b32_e32 v169, 0xffff0000, v180
	v_lshlrev_b32_e32 v170, 16, v181
	v_and_b32_e32 v171, 0xffff0000, v181
	v_lshlrev_b32_e32 v172, 16, v182
	v_and_b32_e32 v173, 0xffff0000, v182
	v_lshlrev_b32_e32 v174, 16, v183
	v_and_b32_e32 v175, 0xffff0000, v183
	v_pk_fma_f32 v[168:169], v[102:103], 0.5, v[168:169] op_sel_hi:[1,0,1]
	v_pk_fma_f32 v[170:171], v[104:105], 0.5, v[170:171] op_sel_hi:[1,0,1]
	v_pk_fma_f32 v[172:173], v[98:99], 0.5, v[172:173] op_sel_hi:[1,0,1]
	v_pk_fma_f32 v[174:175], v[100:101], 0.5, v[174:175] op_sel_hi:[1,0,1]
	v_pk_fma_f32 v[244:245], v[168:169], v[168:169], v[244:245]
	v_pk_fma_f32 v[244:245], v[170:171], v[170:171], v[244:245]
	v_pk_fma_f32 v[244:245], v[172:173], v[172:173], v[244:245]
	v_pk_fma_f32 v[244:245], v[174:175], v[174:175], v[244:245]
	v_cvt_pk_bf16_f32 v180, v168, v169
	v_cvt_pk_bf16_f32 v181, v170, v171
	v_cvt_pk_bf16_f32 v182, v172, v173
	v_cvt_pk_bf16_f32 v183, v174, v175
	global_store_dwordx4 v[164:165], v[180:183], off offset:256
	v_add_f32_e32 v246, v244, v245
	v_mov_b32_e32 v247, v246
	s_nop 1
	v_permlane32_swap_b32 v247, v246
	s_nop 1
	v_add_f32_e32 v246, v246, v247
	v_mov_b32_e32 v247, v246
	s_nop 1
	v_permlane16_swap_b32 v247, v246
	s_nop 1
	v_add_f32_e32 v246, v246, v247
	s_mov_b64 exec, s[46:47]
	global_atomic_add_f32 v[166:167], v246, off offset:64
	s_mov_b64 exec, -1
	s_mov_b64 vcc, 0x8000
	s_nop 0
	v_lshl_add_u64 v[164:165], v[164:165], 0, vcc
	s_waitcnt vmcnt(16)
	v_lshlrev_b32_e32 v168, 16, v184
	v_and_b32_e32 v169, 0xffff0000, v184
	v_lshlrev_b32_e32 v170, 16, v185
	v_and_b32_e32 v171, 0xffff0000, v185
	v_lshlrev_b32_e32 v172, 16, v186
	v_and_b32_e32 v173, 0xffff0000, v186
	v_lshlrev_b32_e32 v174, 16, v187
	v_and_b32_e32 v175, 0xffff0000, v187
	v_pk_fma_f32 v[168:169], v[94:95], 0.5, v[168:169] op_sel_hi:[1,0,1]
	v_pk_fma_f32 v[170:171], v[96:97], 0.5, v[170:171] op_sel_hi:[1,0,1]
	v_pk_fma_f32 v[172:173], v[90:91], 0.5, v[172:173] op_sel_hi:[1,0,1]
	v_pk_fma_f32 v[174:175], v[92:93], 0.5, v[174:175] op_sel_hi:[1,0,1]
	v_pk_mul_f32 v[244:245], v[168:169], v[168:169]
	v_pk_fma_f32 v[244:245], v[170:171], v[170:171], v[244:245]
	v_pk_fma_f32 v[244:245], v[172:173], v[172:173], v[244:245]
	v_pk_fma_f32 v[244:245], v[174:175], v[174:175], v[244:245]
	v_cvt_pk_bf16_f32 v184, v168, v169
	v_cvt_pk_bf16_f32 v185, v170, v171
	v_cvt_pk_bf16_f32 v186, v172, v173
	v_cvt_pk_bf16_f32 v187, v174, v175
	global_store_dwordx4 v[164:165], v[184:187], off
	v_lshlrev_b32_e32 v168, 16, v188
	v_and_b32_e32 v169, 0xffff0000, v188
	v_lshlrev_b32_e32 v170, 16, v189
	v_and_b32_e32 v171, 0xffff0000, v189
	v_lshlrev_b32_e32 v172, 16, v190
	v_and_b32_e32 v173, 0xffff0000, v190
	v_lshlrev_b32_e32 v174, 16, v191
	v_and_b32_e32 v175, 0xffff0000, v191
	v_pk_fma_f32 v[168:169], v[86:87], 0.5, v[168:169] op_sel_hi:[1,0,1]
	v_pk_fma_f32 v[170:171], v[88:89], 0.5, v[170:171] op_sel_hi:[1,0,1]
	v_pk_fma_f32 v[172:173], v[82:83], 0.5, v[172:173] op_sel_hi:[1,0,1]
	v_pk_fma_f32 v[174:175], v[84:85], 0.5, v[174:175] op_sel_hi:[1,0,1]
	v_pk_fma_f32 v[244:245], v[168:169], v[168:169], v[244:245]
	v_pk_fma_f32 v[244:245], v[170:171], v[170:171], v[244:245]
	v_pk_fma_f32 v[244:245], v[172:173], v[172:173], v[244:245]
	v_pk_fma_f32 v[244:245], v[174:175], v[174:175], v[244:245]
	v_cvt_pk_bf16_f32 v188, v168, v169
	v_cvt_pk_bf16_f32 v189, v170, v171
	v_cvt_pk_bf16_f32 v190, v172, v173
	v_cvt_pk_bf16_f32 v191, v174, v175
	global_store_dwordx4 v[164:165], v[188:191], off offset:256
	v_add_f32_e32 v246, v244, v245
	v_mov_b32_e32 v247, v246
	s_nop 1
	v_permlane32_swap_b32 v247, v246
	s_nop 1
	v_add_f32_e32 v246, v246, v247
	v_mov_b32_e32 v247, v246
	s_nop 1
	v_permlane16_swap_b32 v247, v246
	s_nop 1
	v_add_f32_e32 v246, v246, v247
	s_mov_b64 exec, s[46:47]
	global_atomic_add_f32 v[166:167], v246, off offset:128
	s_mov_b64 exec, -1
	s_mov_b64 vcc, 0x8000
	s_nop 0
	v_lshl_add_u64 v[164:165], v[164:165], 0, vcc
	s_waitcnt vmcnt(17)
	v_lshlrev_b32_e32 v168, 16, v204
	v_and_b32_e32 v169, 0xffff0000, v204
	v_lshlrev_b32_e32 v170, 16, v205
	v_and_b32_e32 v171, 0xffff0000, v205
	v_lshlrev_b32_e32 v172, 16, v206
	v_and_b32_e32 v173, 0xffff0000, v206
	v_lshlrev_b32_e32 v174, 16, v207
	v_and_b32_e32 v175, 0xffff0000, v207
	v_pk_fma_f32 v[168:169], v[76:77], 0.5, v[168:169] op_sel_hi:[1,0,1]
	v_pk_fma_f32 v[170:171], v[78:79], 0.5, v[170:171] op_sel_hi:[1,0,1]
	v_pk_fma_f32 v[172:173], v[72:73], 0.5, v[172:173] op_sel_hi:[1,0,1]
	v_pk_fma_f32 v[174:175], v[74:75], 0.5, v[174:175] op_sel_hi:[1,0,1]
	v_pk_mul_f32 v[244:245], v[168:169], v[168:169]
	v_pk_fma_f32 v[244:245], v[170:171], v[170:171], v[244:245]
	v_pk_fma_f32 v[244:245], v[172:173], v[172:173], v[244:245]
	v_pk_fma_f32 v[244:245], v[174:175], v[174:175], v[244:245]
	v_cvt_pk_bf16_f32 v204, v168, v169
	v_cvt_pk_bf16_f32 v205, v170, v171
	v_cvt_pk_bf16_f32 v206, v172, v173
	v_cvt_pk_bf16_f32 v207, v174, v175
	global_store_dwordx4 v[164:165], v[204:207], off
	v_lshlrev_b32_e32 v168, 16, v208
	v_and_b32_e32 v169, 0xffff0000, v208
	v_lshlrev_b32_e32 v170, 16, v209
	v_and_b32_e32 v171, 0xffff0000, v209
	v_lshlrev_b32_e32 v172, 16, v210
	v_and_b32_e32 v173, 0xffff0000, v210
	v_lshlrev_b32_e32 v174, 16, v211
	v_and_b32_e32 v175, 0xffff0000, v211
	v_pk_fma_f32 v[168:169], v[68:69], 0.5, v[168:169] op_sel_hi:[1,0,1]
	v_pk_fma_f32 v[170:171], v[70:71], 0.5, v[170:171] op_sel_hi:[1,0,1]
	v_pk_fma_f32 v[172:173], v[64:65], 0.5, v[172:173] op_sel_hi:[1,0,1]
	v_pk_fma_f32 v[174:175], v[66:67], 0.5, v[174:175] op_sel_hi:[1,0,1]
	v_pk_fma_f32 v[244:245], v[168:169], v[168:169], v[244:245]
	v_pk_fma_f32 v[244:245], v[170:171], v[170:171], v[244:245]
	v_pk_fma_f32 v[244:245], v[172:173], v[172:173], v[244:245]
	v_pk_fma_f32 v[244:245], v[174:175], v[174:175], v[244:245]
	v_cvt_pk_bf16_f32 v208, v168, v169
	v_cvt_pk_bf16_f32 v209, v170, v171
	v_cvt_pk_bf16_f32 v210, v172, v173
	v_cvt_pk_bf16_f32 v211, v174, v175
	global_store_dwordx4 v[164:165], v[208:211], off offset:256
	v_add_f32_e32 v246, v244, v245
	v_mov_b32_e32 v247, v246
	s_nop 1
	v_permlane32_swap_b32 v247, v246
	s_nop 1
	v_add_f32_e32 v246, v246, v247
	v_mov_b32_e32 v247, v246
	s_nop 1
	v_permlane16_swap_b32 v247, v246
	s_nop 1
	v_add_f32_e32 v246, v246, v247
	s_mov_b64 exec, s[46:47]
	global_atomic_add_f32 v[166:167], v246, off offset:192
	s_mov_b64 exec, -1
	s_mov_b64 vcc, 0x28000
	s_nop 0
	v_lshl_add_u64 v[164:165], v[164:165], 0, vcc
	s_waitcnt vmcnt(18)
	v_lshlrev_b32_e32 v168, 16, v212
	v_and_b32_e32 v169, 0xffff0000, v212
	v_lshlrev_b32_e32 v170, 16, v213
	v_and_b32_e32 v171, 0xffff0000, v213
	v_lshlrev_b32_e32 v172, 16, v214
	v_and_b32_e32 v173, 0xffff0000, v214
	v_lshlrev_b32_e32 v174, 16, v215
	v_and_b32_e32 v175, 0xffff0000, v215
	v_pk_fma_f32 v[168:169], v[60:61], 0.5, v[168:169] op_sel_hi:[1,0,1]
	v_pk_fma_f32 v[170:171], v[62:63], 0.5, v[170:171] op_sel_hi:[1,0,1]
	v_pk_fma_f32 v[172:173], v[56:57], 0.5, v[172:173] op_sel_hi:[1,0,1]
	v_pk_fma_f32 v[174:175], v[58:59], 0.5, v[174:175] op_sel_hi:[1,0,1]
	v_pk_mul_f32 v[244:245], v[168:169], v[168:169]
	v_pk_fma_f32 v[244:245], v[170:171], v[170:171], v[244:245]
	v_pk_fma_f32 v[244:245], v[172:173], v[172:173], v[244:245]
	v_pk_fma_f32 v[244:245], v[174:175], v[174:175], v[244:245]
	v_cvt_pk_bf16_f32 v212, v168, v169
	v_cvt_pk_bf16_f32 v213, v170, v171
	v_cvt_pk_bf16_f32 v214, v172, v173
	v_cvt_pk_bf16_f32 v215, v174, v175
	global_store_dwordx4 v[164:165], v[212:215], off
	v_lshlrev_b32_e32 v168, 16, v216
	v_and_b32_e32 v169, 0xffff0000, v216
	v_lshlrev_b32_e32 v170, 16, v217
	v_and_b32_e32 v171, 0xffff0000, v217
	v_lshlrev_b32_e32 v172, 16, v218
	v_and_b32_e32 v173, 0xffff0000, v218
	v_lshlrev_b32_e32 v174, 16, v219
	v_and_b32_e32 v175, 0xffff0000, v219
	v_pk_fma_f32 v[168:169], v[52:53], 0.5, v[168:169] op_sel_hi:[1,0,1]
	v_pk_fma_f32 v[170:171], v[54:55], 0.5, v[170:171] op_sel_hi:[1,0,1]
	v_pk_fma_f32 v[172:173], v[48:49], 0.5, v[172:173] op_sel_hi:[1,0,1]
	v_pk_fma_f32 v[174:175], v[50:51], 0.5, v[174:175] op_sel_hi:[1,0,1]
	v_pk_fma_f32 v[244:245], v[168:169], v[168:169], v[244:245]
	v_pk_fma_f32 v[244:245], v[170:171], v[170:171], v[244:245]
	v_pk_fma_f32 v[244:245], v[172:173], v[172:173], v[244:245]
	v_pk_fma_f32 v[244:245], v[174:175], v[174:175], v[244:245]
	v_cvt_pk_bf16_f32 v216, v168, v169
	v_cvt_pk_bf16_f32 v217, v170, v171
	v_cvt_pk_bf16_f32 v218, v172, v173
	v_cvt_pk_bf16_f32 v219, v174, v175
	global_store_dwordx4 v[164:165], v[216:219], off offset:256
	v_add_f32_e32 v246, v244, v245
	v_mov_b32_e32 v247, v246
	s_nop 1
	v_permlane32_swap_b32 v247, v246
	s_nop 1
	v_add_f32_e32 v246, v246, v247
	v_mov_b32_e32 v247, v246
	s_nop 1
	v_permlane16_swap_b32 v247, v246
	s_nop 1
	v_add_f32_e32 v246, v246, v247
	s_mov_b64 exec, s[46:47]
	global_atomic_add_f32 v[166:167], v246, off offset:512
	s_mov_b64 exec, -1
	s_mov_b64 vcc, 0x8000
	s_nop 0
	v_lshl_add_u64 v[164:165], v[164:165], 0, vcc
	s_waitcnt vmcnt(19)
	v_lshlrev_b32_e32 v168, 16, v220
	v_and_b32_e32 v169, 0xffff0000, v220
	v_lshlrev_b32_e32 v170, 16, v221
	v_and_b32_e32 v171, 0xffff0000, v221
	v_lshlrev_b32_e32 v172, 16, v222
	v_and_b32_e32 v173, 0xffff0000, v222
	v_lshlrev_b32_e32 v174, 16, v223
	v_and_b32_e32 v175, 0xffff0000, v223
	v_pk_fma_f32 v[168:169], v[44:45], 0.5, v[168:169] op_sel_hi:[1,0,1]
	v_pk_fma_f32 v[170:171], v[46:47], 0.5, v[170:171] op_sel_hi:[1,0,1]
	v_pk_fma_f32 v[172:173], v[40:41], 0.5, v[172:173] op_sel_hi:[1,0,1]
	v_pk_fma_f32 v[174:175], v[42:43], 0.5, v[174:175] op_sel_hi:[1,0,1]
	v_pk_mul_f32 v[244:245], v[168:169], v[168:169]
	v_pk_fma_f32 v[244:245], v[170:171], v[170:171], v[244:245]
	v_pk_fma_f32 v[244:245], v[172:173], v[172:173], v[244:245]
	v_pk_fma_f32 v[244:245], v[174:175], v[174:175], v[244:245]
	v_cvt_pk_bf16_f32 v220, v168, v169
	v_cvt_pk_bf16_f32 v221, v170, v171
	v_cvt_pk_bf16_f32 v222, v172, v173
	v_cvt_pk_bf16_f32 v223, v174, v175
	global_store_dwordx4 v[164:165], v[220:223], off
	v_lshlrev_b32_e32 v168, 16, v224
	v_and_b32_e32 v169, 0xffff0000, v224
	v_lshlrev_b32_e32 v170, 16, v225
	v_and_b32_e32 v171, 0xffff0000, v225
	v_lshlrev_b32_e32 v172, 16, v226
	v_and_b32_e32 v173, 0xffff0000, v226
	v_lshlrev_b32_e32 v174, 16, v227
	v_and_b32_e32 v175, 0xffff0000, v227
	v_pk_fma_f32 v[168:169], v[36:37], 0.5, v[168:169] op_sel_hi:[1,0,1]
	v_pk_fma_f32 v[170:171], v[38:39], 0.5, v[170:171] op_sel_hi:[1,0,1]
	v_pk_fma_f32 v[172:173], v[32:33], 0.5, v[172:173] op_sel_hi:[1,0,1]
	v_pk_fma_f32 v[174:175], v[34:35], 0.5, v[174:175] op_sel_hi:[1,0,1]
	v_pk_fma_f32 v[244:245], v[168:169], v[168:169], v[244:245]
	v_pk_fma_f32 v[244:245], v[170:171], v[170:171], v[244:245]
	v_pk_fma_f32 v[244:245], v[172:173], v[172:173], v[244:245]
	v_pk_fma_f32 v[244:245], v[174:175], v[174:175], v[244:245]
	v_cvt_pk_bf16_f32 v224, v168, v169
	v_cvt_pk_bf16_f32 v225, v170, v171
	v_cvt_pk_bf16_f32 v226, v172, v173
	v_cvt_pk_bf16_f32 v227, v174, v175
	global_store_dwordx4 v[164:165], v[224:227], off offset:256
	v_add_f32_e32 v246, v244, v245
	v_mov_b32_e32 v247, v246
	s_nop 1
	v_permlane32_swap_b32 v247, v246
	s_nop 1
	v_add_f32_e32 v246, v246, v247
	v_mov_b32_e32 v247, v246
	s_nop 1
	v_permlane16_swap_b32 v247, v246
	s_nop 1
	v_add_f32_e32 v246, v246, v247
	s_mov_b64 exec, s[46:47]
	global_atomic_add_f32 v[166:167], v246, off offset:576
	s_mov_b64 exec, -1
	s_mov_b64 vcc, 0x8000
	s_nop 0
	v_lshl_add_u64 v[164:165], v[164:165], 0, vcc
	s_waitcnt vmcnt(20)
	v_lshlrev_b32_e32 v168, 16, v228
	v_and_b32_e32 v169, 0xffff0000, v228
	v_lshlrev_b32_e32 v170, 16, v229
	v_and_b32_e32 v171, 0xffff0000, v229
	v_lshlrev_b32_e32 v172, 16, v230
	v_and_b32_e32 v173, 0xffff0000, v230
	v_lshlrev_b32_e32 v174, 16, v231
	v_and_b32_e32 v175, 0xffff0000, v231
	v_pk_fma_f32 v[168:169], v[28:29], 0.5, v[168:169] op_sel_hi:[1,0,1]
	v_pk_fma_f32 v[170:171], v[30:31], 0.5, v[170:171] op_sel_hi:[1,0,1]
	v_pk_fma_f32 v[172:173], v[24:25], 0.5, v[172:173] op_sel_hi:[1,0,1]
	v_pk_fma_f32 v[174:175], v[26:27], 0.5, v[174:175] op_sel_hi:[1,0,1]
	v_pk_mul_f32 v[244:245], v[168:169], v[168:169]
	v_pk_fma_f32 v[244:245], v[170:171], v[170:171], v[244:245]
	v_pk_fma_f32 v[244:245], v[172:173], v[172:173], v[244:245]
	v_pk_fma_f32 v[244:245], v[174:175], v[174:175], v[244:245]
	v_cvt_pk_bf16_f32 v228, v168, v169
	v_cvt_pk_bf16_f32 v229, v170, v171
	v_cvt_pk_bf16_f32 v230, v172, v173
	v_cvt_pk_bf16_f32 v231, v174, v175
	global_store_dwordx4 v[164:165], v[228:231], off
	v_lshlrev_b32_e32 v168, 16, v232
	v_and_b32_e32 v169, 0xffff0000, v232
	v_lshlrev_b32_e32 v170, 16, v233
	v_and_b32_e32 v171, 0xffff0000, v233
	v_lshlrev_b32_e32 v172, 16, v234
	v_and_b32_e32 v173, 0xffff0000, v234
	v_lshlrev_b32_e32 v174, 16, v235
	v_and_b32_e32 v175, 0xffff0000, v235
	v_pk_fma_f32 v[168:169], v[20:21], 0.5, v[168:169] op_sel_hi:[1,0,1]
	v_pk_fma_f32 v[170:171], v[22:23], 0.5, v[170:171] op_sel_hi:[1,0,1]
	v_pk_fma_f32 v[172:173], v[16:17], 0.5, v[172:173] op_sel_hi:[1,0,1]
	v_pk_fma_f32 v[174:175], v[18:19], 0.5, v[174:175] op_sel_hi:[1,0,1]
	v_pk_fma_f32 v[244:245], v[168:169], v[168:169], v[244:245]
	v_pk_fma_f32 v[244:245], v[170:171], v[170:171], v[244:245]
	v_pk_fma_f32 v[244:245], v[172:173], v[172:173], v[244:245]
	v_pk_fma_f32 v[244:245], v[174:175], v[174:175], v[244:245]
	v_cvt_pk_bf16_f32 v232, v168, v169
	v_cvt_pk_bf16_f32 v233, v170, v171
	v_cvt_pk_bf16_f32 v234, v172, v173
	v_cvt_pk_bf16_f32 v235, v174, v175
	global_store_dwordx4 v[164:165], v[232:235], off offset:256
	v_add_f32_e32 v246, v244, v245
	v_mov_b32_e32 v247, v246
	s_nop 1
	v_permlane32_swap_b32 v247, v246
	s_nop 1
	v_add_f32_e32 v246, v246, v247
	v_mov_b32_e32 v247, v246
	s_nop 1
	v_permlane16_swap_b32 v247, v246
	s_nop 1
	v_add_f32_e32 v246, v246, v247
	s_mov_b64 exec, s[46:47]
	global_atomic_add_f32 v[166:167], v246, off offset:640
	s_mov_b64 exec, -1
	s_mov_b64 vcc, 0x8000
	s_nop 0
	v_lshl_add_u64 v[164:165], v[164:165], 0, vcc
	s_waitcnt vmcnt(21)
	v_lshlrev_b32_e32 v168, 16, v236
	v_and_b32_e32 v169, 0xffff0000, v236
	v_lshlrev_b32_e32 v170, 16, v237
	v_and_b32_e32 v171, 0xffff0000, v237
	v_lshlrev_b32_e32 v172, 16, v238
	v_and_b32_e32 v173, 0xffff0000, v238
	v_lshlrev_b32_e32 v174, 16, v239
	v_and_b32_e32 v175, 0xffff0000, v239
	v_pk_fma_f32 v[168:169], v[12:13], 0.5, v[168:169] op_sel_hi:[1,0,1]
	v_pk_fma_f32 v[170:171], v[14:15], 0.5, v[170:171] op_sel_hi:[1,0,1]
	v_pk_fma_f32 v[172:173], v[8:9], 0.5, v[172:173] op_sel_hi:[1,0,1]
	v_pk_fma_f32 v[174:175], v[10:11], 0.5, v[174:175] op_sel_hi:[1,0,1]
	v_pk_mul_f32 v[244:245], v[168:169], v[168:169]
	v_pk_fma_f32 v[244:245], v[170:171], v[170:171], v[244:245]
	v_pk_fma_f32 v[244:245], v[172:173], v[172:173], v[244:245]
	v_pk_fma_f32 v[244:245], v[174:175], v[174:175], v[244:245]
	v_cvt_pk_bf16_f32 v236, v168, v169
	v_cvt_pk_bf16_f32 v237, v170, v171
	v_cvt_pk_bf16_f32 v238, v172, v173
	v_cvt_pk_bf16_f32 v239, v174, v175
	global_store_dwordx4 v[164:165], v[236:239], off
	v_lshlrev_b32_e32 v168, 16, v240
	v_and_b32_e32 v169, 0xffff0000, v240
	v_lshlrev_b32_e32 v170, 16, v241
	v_and_b32_e32 v171, 0xffff0000, v241
	v_lshlrev_b32_e32 v172, 16, v242
	v_and_b32_e32 v173, 0xffff0000, v242
	v_lshlrev_b32_e32 v174, 16, v243
	v_and_b32_e32 v175, 0xffff0000, v243
	v_pk_fma_f32 v[168:169], v[4:5], 0.5, v[168:169] op_sel_hi:[1,0,1]
	v_pk_fma_f32 v[170:171], v[6:7], 0.5, v[170:171] op_sel_hi:[1,0,1]
	v_pk_fma_f32 v[172:173], v[0:1], 0.5, v[172:173] op_sel_hi:[1,0,1]
	v_pk_fma_f32 v[174:175], v[2:3], 0.5, v[174:175] op_sel_hi:[1,0,1]
	v_pk_fma_f32 v[244:245], v[168:169], v[168:169], v[244:245]
	v_pk_fma_f32 v[244:245], v[170:171], v[170:171], v[244:245]
	v_pk_fma_f32 v[244:245], v[172:173], v[172:173], v[244:245]
	v_pk_fma_f32 v[244:245], v[174:175], v[174:175], v[244:245]
	v_cvt_pk_bf16_f32 v240, v168, v169
	v_cvt_pk_bf16_f32 v241, v170, v171
	v_cvt_pk_bf16_f32 v242, v172, v173
	v_cvt_pk_bf16_f32 v243, v174, v175
	global_store_dwordx4 v[164:165], v[240:243], off offset:256
	v_add_f32_e32 v246, v244, v245
	v_mov_b32_e32 v247, v246
	s_nop 1
	v_permlane32_swap_b32 v247, v246
	s_nop 1
	v_add_f32_e32 v246, v246, v247
	v_mov_b32_e32 v247, v246
	s_nop 1
	v_permlane16_swap_b32 v247, v246
	s_nop 1
	v_add_f32_e32 v246, v246, v247
	s_mov_b64 exec, s[46:47]
	global_atomic_add_f32 v[166:167], v246, off offset:704
	s_mov_b64 exec, -1
	s_mov_b64 s[40:41], exec
	s_branch .LBB0_212

.LBB0_643:
	v_ashrrev_i32_e32 v142, 2, v192
	v_and_b32_e32 v142, 0xffffffc0, v142
	s_lshl_b32 vcc_lo, s53, 8
	v_and_or_b32 v143, v192, 15, vcc_lo
	v_add_u32_e32 v142, v143, v142
	v_ashrrev_i32_e32 v143, 31, v142
	v_bfe_u32 v147, v192, 4, 2
	v_lshrrev_b32_e32 v80, 1, v192
	v_and_b32_e32 v80, 0x60, v80
	s_lshl_b32 vcc_lo, s52, 8
	v_add_u32_e32 v80, vcc_lo, v80
	v_lshl_add_u32 v80, v147, 3, v80
	v_lshlrev_b32_e32 v80, 1, v80
	v_lshlrev_b64 v[164:165], 11, v[142:143]
	v_lshl_add_u64 v[164:165], s[38:39], 0, v[164:165]
	v_lshl_add_u64 v[164:165], v[164:165], 0, v[80:81]
	v_mov_b32_e32 v248, v164
	v_mov_b32_e32 v249, v165
	global_load_dwordx4 v[148:151], v[248:249], off
	global_load_dwordx4 v[160:163], v[248:249], off offset:256
	s_mov_b64 vcc, 0x8000
	s_nop 0
	v_lshl_add_u64 v[248:249], v[248:249], 0, vcc
	global_load_dwordx4 v[176:179], v[248:249], off
	global_load_dwordx4 v[180:183], v[248:249], off offset:256
	s_mov_b64 vcc, 0x8000
	s_nop 0
	v_lshl_add_u64 v[248:249], v[248:249], 0, vcc
	global_load_dwordx4 v[184:187], v[248:249], off
	global_load_dwordx4 v[188:191], v[248:249], off offset:256
	s_mov_b64 vcc, 0x8000
	s_nop 0
	v_lshl_add_u64 v[248:249], v[248:249], 0, vcc
	global_load_dwordx4 v[204:207], v[248:249], off
	global_load_dwordx4 v[208:211], v[248:249], off offset:256
	s_mov_b64 vcc, 0x28000
	s_nop 0
	v_lshl_add_u64 v[248:249], v[248:249], 0, vcc
	global_load_dwordx4 v[212:215], v[248:249], off
	global_load_dwordx4 v[216:219], v[248:249], off offset:256
	s_mov_b64 vcc, 0x8000
	s_nop 0
	v_lshl_add_u64 v[248:249], v[248:249], 0, vcc
	global_load_dwordx4 v[220:223], v[248:249], off
	global_load_dwordx4 v[224:227], v[248:249], off offset:256
	s_mov_b64 vcc, 0x8000
	s_nop 0
	v_lshl_add_u64 v[248:249], v[248:249], 0, vcc
	global_load_dwordx4 v[228:231], v[248:249], off
	global_load_dwordx4 v[232:235], v[248:249], off offset:256
	s_mov_b64 vcc, 0x8000
	s_nop 0
	v_lshl_add_u64 v[248:249], v[248:249], 0, vcc
	global_load_dwordx4 v[236:239], v[248:249], off
	global_load_dwordx4 v[240:243], v[248:249], off offset:256
	v_cmp_eq_u32_e64 s[46:47], 0, v147
	s_nop 0
	v_lshl_add_u64 v[166:167], v[142:143], 2, s[26:27]
	s_waitcnt vmcnt(14)
	v_lshlrev_b32_e32 v168, 16, v148
	v_and_b32_e32 v169, 0xffff0000, v148
	v_lshlrev_b32_e32 v170, 16, v149
	v_and_b32_e32 v171, 0xffff0000, v149
	v_lshlrev_b32_e32 v172, 16, v150
	v_and_b32_e32 v173, 0xffff0000, v150
	v_lshlrev_b32_e32 v174, 16, v151
	v_and_b32_e32 v175, 0xffff0000, v151
	v_pk_fma_f32 v[168:169], v[126:127], 0.5, v[168:169] op_sel_hi:[1,0,1]
	v_pk_fma_f32 v[170:171], v[128:129], 0.5, v[170:171] op_sel_hi:[1,0,1]
	v_pk_fma_f32 v[172:173], v[122:123], 0.5, v[172:173] op_sel_hi:[1,0,1]
	v_pk_fma_f32 v[174:175], v[124:125], 0.5, v[174:175] op_sel_hi:[1,0,1]
	v_pk_mul_f32 v[244:245], v[168:169], v[168:169]
	v_pk_fma_f32 v[244:245], v[170:171], v[170:171], v[244:245]
	v_pk_fma_f32 v[244:245], v[172:173], v[172:173], v[244:245]
	v_pk_fma_f32 v[244:245], v[174:175], v[174:175], v[244:245]
	v_cvt_pk_bf16_f32 v148, v168, v169
	v_cvt_pk_bf16_f32 v149, v170, v171
	v_cvt_pk_bf16_f32 v150, v172, v173
	v_cvt_pk_bf16_f32 v151, v174, v175
	global_store_dwordx4 v[164:165], v[148:151], off
	v_lshlrev_b32_e32 v168, 16, v160
	v_and_b32_e32 v169, 0xffff0000, v160
	v_lshlrev_b32_e32 v170, 16, v161
	v_and_b32_e32 v171, 0xffff0000, v161
	v_lshlrev_b32_e32 v172, 16, v162
	v_and_b32_e32 v173, 0xffff0000, v162
	v_lshlrev_b32_e32 v174, 16, v163
	v_and_b32_e32 v175, 0xffff0000, v163
	v_pk_fma_f32 v[168:169], v[118:119], 0.5, v[168:169] op_sel_hi:[1,0,1]
	v_pk_fma_f32 v[170:171], v[120:121], 0.5, v[170:171] op_sel_hi:[1,0,1]
	v_pk_fma_f32 v[172:173], v[114:115], 0.5, v[172:173] op_sel_hi:[1,0,1]
	v_pk_fma_f32 v[174:175], v[116:117], 0.5, v[174:175] op_sel_hi:[1,0,1]
	v_pk_fma_f32 v[244:245], v[168:169], v[168:169], v[244:245]
	v_pk_fma_f32 v[244:245], v[170:171], v[170:171], v[244:245]
	v_pk_fma_f32 v[244:245], v[172:173], v[172:173], v[244:245]
	v_pk_fma_f32 v[244:245], v[174:175], v[174:175], v[244:245]
	v_cvt_pk_bf16_f32 v160, v168, v169
	v_cvt_pk_bf16_f32 v161, v170, v171
	v_cvt_pk_bf16_f32 v162, v172, v173
	v_cvt_pk_bf16_f32 v163, v174, v175
	global_store_dwordx4 v[164:165], v[160:163], off offset:256
	v_add_f32_e32 v246, v244, v245
	v_mov_b32_e32 v247, v246
	s_nop 1
	v_permlane32_swap_b32 v247, v246
	s_nop 1
	v_add_f32_e32 v246, v246, v247
	v_mov_b32_e32 v247, v246
	s_nop 1
	v_permlane16_swap_b32 v247, v246
	s_nop 1
	v_add_f32_e32 v246, v246, v247
	s_mov_b64 exec, s[46:47]
	global_atomic_add_f32 v[166:167], v246, off
	s_mov_b64 exec, -1
	s_mov_b64 vcc, 0x8000
	s_nop 0
	v_lshl_add_u64 v[164:165], v[164:165], 0, vcc
	s_waitcnt vmcnt(15)
	v_lshlrev_b32_e32 v168, 16, v176
	v_and_b32_e32 v169, 0xffff0000, v176
	v_lshlrev_b32_e32 v170, 16, v177
	v_and_b32_e32 v171, 0xffff0000, v177
	v_lshlrev_b32_e32 v172, 16, v178
	v_and_b32_e32 v173, 0xffff0000, v178
	v_lshlrev_b32_e32 v174, 16, v179
	v_and_b32_e32 v175, 0xffff0000, v179
	v_pk_fma_f32 v[168:169], v[110:111], 0.5, v[168:169] op_sel_hi:[1,0,1]
	v_pk_fma_f32 v[170:171], v[112:113], 0.5, v[170:171] op_sel_hi:[1,0,1]
	v_pk_fma_f32 v[172:173], v[106:107], 0.5, v[172:173] op_sel_hi:[1,0,1]
	v_pk_fma_f32 v[174:175], v[108:109], 0.5, v[174:175] op_sel_hi:[1,0,1]
	v_pk_mul_f32 v[244:245], v[168:169], v[168:169]
	v_pk_fma_f32 v[244:245], v[170:171], v[170:171], v[244:245]
	v_pk_fma_f32 v[244:245], v[172:173], v[172:173], v[244:245]
	v_pk_fma_f32 v[244:245], v[174:175], v[174:175], v[244:245]
	v_cvt_pk_bf16_f32 v176, v168, v169
	v_cvt_pk_bf16_f32 v177, v170, v171
	v_cvt_pk_bf16_f32 v178, v172, v173
	v_cvt_pk_bf16_f32 v179, v174, v175
	global_store_dwordx4 v[164:165], v[176:179], off
	v_lshlrev_b32_e32 v168, 16, v180
	v_and_b32_e32 v169, 0xffff0000, v180
	v_lshlrev_b32_e32 v170, 16, v181
	v_and_b32_e32 v171, 0xffff0000, v181
	v_lshlrev_b32_e32 v172, 16, v182
	v_and_b32_e32 v173, 0xffff0000, v182
	v_lshlrev_b32_e32 v174, 16, v183
	v_and_b32_e32 v175, 0xffff0000, v183
	v_pk_fma_f32 v[168:169], v[102:103], 0.5, v[168:169] op_sel_hi:[1,0,1]
	v_pk_fma_f32 v[170:171], v[104:105], 0.5, v[170:171] op_sel_hi:[1,0,1]
	v_pk_fma_f32 v[172:173], v[98:99], 0.5, v[172:173] op_sel_hi:[1,0,1]
	v_pk_fma_f32 v[174:175], v[100:101], 0.5, v[174:175] op_sel_hi:[1,0,1]
	v_pk_fma_f32 v[244:245], v[168:169], v[168:169], v[244:245]
	v_pk_fma_f32 v[244:245], v[170:171], v[170:171], v[244:245]
	v_pk_fma_f32 v[244:245], v[172:173], v[172:173], v[244:245]
	v_pk_fma_f32 v[244:245], v[174:175], v[174:175], v[244:245]
	v_cvt_pk_bf16_f32 v180, v168, v169
	v_cvt_pk_bf16_f32 v181, v170, v171
	v_cvt_pk_bf16_f32 v182, v172, v173
	v_cvt_pk_bf16_f32 v183, v174, v175
	global_store_dwordx4 v[164:165], v[180:183], off offset:256
	v_add_f32_e32 v246, v244, v245
	v_mov_b32_e32 v247, v246
	s_nop 1
	v_permlane32_swap_b32 v247, v246
	s_nop 1
	v_add_f32_e32 v246, v246, v247
	v_mov_b32_e32 v247, v246
	s_nop 1
	v_permlane16_swap_b32 v247, v246
	s_nop 1
	v_add_f32_e32 v246, v246, v247
	s_mov_b64 exec, s[46:47]
	global_atomic_add_f32 v[166:167], v246, off offset:64
	s_mov_b64 exec, -1
	s_mov_b64 vcc, 0x8000
	s_nop 0
	v_lshl_add_u64 v[164:165], v[164:165], 0, vcc
	s_waitcnt vmcnt(16)
	v_lshlrev_b32_e32 v168, 16, v184
	v_and_b32_e32 v169, 0xffff0000, v184
	v_lshlrev_b32_e32 v170, 16, v185
	v_and_b32_e32 v171, 0xffff0000, v185
	v_lshlrev_b32_e32 v172, 16, v186
	v_and_b32_e32 v173, 0xffff0000, v186
	v_lshlrev_b32_e32 v174, 16, v187
	v_and_b32_e32 v175, 0xffff0000, v187
	v_pk_fma_f32 v[168:169], v[94:95], 0.5, v[168:169] op_sel_hi:[1,0,1]
	v_pk_fma_f32 v[170:171], v[96:97], 0.5, v[170:171] op_sel_hi:[1,0,1]
	v_pk_fma_f32 v[172:173], v[90:91], 0.5, v[172:173] op_sel_hi:[1,0,1]
	v_pk_fma_f32 v[174:175], v[92:93], 0.5, v[174:175] op_sel_hi:[1,0,1]
	v_pk_mul_f32 v[244:245], v[168:169], v[168:169]
	v_pk_fma_f32 v[244:245], v[170:171], v[170:171], v[244:245]
	v_pk_fma_f32 v[244:245], v[172:173], v[172:173], v[244:245]
	v_pk_fma_f32 v[244:245], v[174:175], v[174:175], v[244:245]
	v_cvt_pk_bf16_f32 v184, v168, v169
	v_cvt_pk_bf16_f32 v185, v170, v171
	v_cvt_pk_bf16_f32 v186, v172, v173
	v_cvt_pk_bf16_f32 v187, v174, v175
	global_store_dwordx4 v[164:165], v[184:187], off
	v_lshlrev_b32_e32 v168, 16, v188
	v_and_b32_e32 v169, 0xffff0000, v188
	v_lshlrev_b32_e32 v170, 16, v189
	v_and_b32_e32 v171, 0xffff0000, v189
	v_lshlrev_b32_e32 v172, 16, v190
	v_and_b32_e32 v173, 0xffff0000, v190
	v_lshlrev_b32_e32 v174, 16, v191
	v_and_b32_e32 v175, 0xffff0000, v191
	v_pk_fma_f32 v[168:169], v[86:87], 0.5, v[168:169] op_sel_hi:[1,0,1]
	v_pk_fma_f32 v[170:171], v[88:89], 0.5, v[170:171] op_sel_hi:[1,0,1]
	v_pk_fma_f32 v[172:173], v[82:83], 0.5, v[172:173] op_sel_hi:[1,0,1]
	v_pk_fma_f32 v[174:175], v[84:85], 0.5, v[174:175] op_sel_hi:[1,0,1]
	v_pk_fma_f32 v[244:245], v[168:169], v[168:169], v[244:245]
	v_pk_fma_f32 v[244:245], v[170:171], v[170:171], v[244:245]
	v_pk_fma_f32 v[244:245], v[172:173], v[172:173], v[244:245]
	v_pk_fma_f32 v[244:245], v[174:175], v[174:175], v[244:245]
	v_cvt_pk_bf16_f32 v188, v168, v169
	v_cvt_pk_bf16_f32 v189, v170, v171
	v_cvt_pk_bf16_f32 v190, v172, v173
	v_cvt_pk_bf16_f32 v191, v174, v175
	global_store_dwordx4 v[164:165], v[188:191], off offset:256
	v_add_f32_e32 v246, v244, v245
	v_mov_b32_e32 v247, v246
	s_nop 1
	v_permlane32_swap_b32 v247, v246
	s_nop 1
	v_add_f32_e32 v246, v246, v247
	v_mov_b32_e32 v247, v246
	s_nop 1
	v_permlane16_swap_b32 v247, v246
	s_nop 1
	v_add_f32_e32 v246, v246, v247
	s_mov_b64 exec, s[46:47]
	global_atomic_add_f32 v[166:167], v246, off offset:128
	s_mov_b64 exec, -1
	s_mov_b64 vcc, 0x8000
	s_nop 0
	v_lshl_add_u64 v[164:165], v[164:165], 0, vcc
	s_waitcnt vmcnt(17)
	v_lshlrev_b32_e32 v168, 16, v204
	v_and_b32_e32 v169, 0xffff0000, v204
	v_lshlrev_b32_e32 v170, 16, v205
	v_and_b32_e32 v171, 0xffff0000, v205
	v_lshlrev_b32_e32 v172, 16, v206
	v_and_b32_e32 v173, 0xffff0000, v206
	v_lshlrev_b32_e32 v174, 16, v207
	v_and_b32_e32 v175, 0xffff0000, v207
	v_pk_fma_f32 v[168:169], v[76:77], 0.5, v[168:169] op_sel_hi:[1,0,1]
	v_pk_fma_f32 v[170:171], v[78:79], 0.5, v[170:171] op_sel_hi:[1,0,1]
	v_pk_fma_f32 v[172:173], v[72:73], 0.5, v[172:173] op_sel_hi:[1,0,1]
	v_pk_fma_f32 v[174:175], v[74:75], 0.5, v[174:175] op_sel_hi:[1,0,1]
	v_pk_mul_f32 v[244:245], v[168:169], v[168:169]
	v_pk_fma_f32 v[244:245], v[170:171], v[170:171], v[244:245]
	v_pk_fma_f32 v[244:245], v[172:173], v[172:173], v[244:245]
	v_pk_fma_f32 v[244:245], v[174:175], v[174:175], v[244:245]
	v_cvt_pk_bf16_f32 v204, v168, v169
	v_cvt_pk_bf16_f32 v205, v170, v171
	v_cvt_pk_bf16_f32 v206, v172, v173
	v_cvt_pk_bf16_f32 v207, v174, v175
	global_store_dwordx4 v[164:165], v[204:207], off
	v_lshlrev_b32_e32 v168, 16, v208
	v_and_b32_e32 v169, 0xffff0000, v208
	v_lshlrev_b32_e32 v170, 16, v209
	v_and_b32_e32 v171, 0xffff0000, v209
	v_lshlrev_b32_e32 v172, 16, v210
	v_and_b32_e32 v173, 0xffff0000, v210
	v_lshlrev_b32_e32 v174, 16, v211
	v_and_b32_e32 v175, 0xffff0000, v211
	v_pk_fma_f32 v[168:169], v[68:69], 0.5, v[168:169] op_sel_hi:[1,0,1]
	v_pk_fma_f32 v[170:171], v[70:71], 0.5, v[170:171] op_sel_hi:[1,0,1]
	v_pk_fma_f32 v[172:173], v[64:65], 0.5, v[172:173] op_sel_hi:[1,0,1]
	v_pk_fma_f32 v[174:175], v[66:67], 0.5, v[174:175] op_sel_hi:[1,0,1]
	v_pk_fma_f32 v[244:245], v[168:169], v[168:169], v[244:245]
	v_pk_fma_f32 v[244:245], v[170:171], v[170:171], v[244:245]
	v_pk_fma_f32 v[244:245], v[172:173], v[172:173], v[244:245]
	v_pk_fma_f32 v[244:245], v[174:175], v[174:175], v[244:245]
	v_cvt_pk_bf16_f32 v208, v168, v169
	v_cvt_pk_bf16_f32 v209, v170, v171
	v_cvt_pk_bf16_f32 v210, v172, v173
	v_cvt_pk_bf16_f32 v211, v174, v175
	global_store_dwordx4 v[164:165], v[208:211], off offset:256
	v_add_f32_e32 v246, v244, v245
	v_mov_b32_e32 v247, v246
	s_nop 1
	v_permlane32_swap_b32 v247, v246
	s_nop 1
	v_add_f32_e32 v246, v246, v247
	v_mov_b32_e32 v247, v246
	s_nop 1
	v_permlane16_swap_b32 v247, v246
	s_nop 1
	v_add_f32_e32 v246, v246, v247
	s_mov_b64 exec, s[46:47]
	global_atomic_add_f32 v[166:167], v246, off offset:192
	s_mov_b64 exec, -1
	s_mov_b64 vcc, 0x28000
	s_nop 0
	v_lshl_add_u64 v[164:165], v[164:165], 0, vcc
	s_waitcnt vmcnt(18)
	v_lshlrev_b32_e32 v168, 16, v212
	v_and_b32_e32 v169, 0xffff0000, v212
	v_lshlrev_b32_e32 v170, 16, v213
	v_and_b32_e32 v171, 0xffff0000, v213
	v_lshlrev_b32_e32 v172, 16, v214
	v_and_b32_e32 v173, 0xffff0000, v214
	v_lshlrev_b32_e32 v174, 16, v215
	v_and_b32_e32 v175, 0xffff0000, v215
	v_pk_fma_f32 v[168:169], v[60:61], 0.5, v[168:169] op_sel_hi:[1,0,1]
	v_pk_fma_f32 v[170:171], v[62:63], 0.5, v[170:171] op_sel_hi:[1,0,1]
	v_pk_fma_f32 v[172:173], v[56:57], 0.5, v[172:173] op_sel_hi:[1,0,1]
	v_pk_fma_f32 v[174:175], v[58:59], 0.5, v[174:175] op_sel_hi:[1,0,1]
	v_pk_mul_f32 v[244:245], v[168:169], v[168:169]
	v_pk_fma_f32 v[244:245], v[170:171], v[170:171], v[244:245]
	v_pk_fma_f32 v[244:245], v[172:173], v[172:173], v[244:245]
	v_pk_fma_f32 v[244:245], v[174:175], v[174:175], v[244:245]
	v_cvt_pk_bf16_f32 v212, v168, v169
	v_cvt_pk_bf16_f32 v213, v170, v171
	v_cvt_pk_bf16_f32 v214, v172, v173
	v_cvt_pk_bf16_f32 v215, v174, v175
	global_store_dwordx4 v[164:165], v[212:215], off
	v_lshlrev_b32_e32 v168, 16, v216
	v_and_b32_e32 v169, 0xffff0000, v216
	v_lshlrev_b32_e32 v170, 16, v217
	v_and_b32_e32 v171, 0xffff0000, v217
	v_lshlrev_b32_e32 v172, 16, v218
	v_and_b32_e32 v173, 0xffff0000, v218
	v_lshlrev_b32_e32 v174, 16, v219
	v_and_b32_e32 v175, 0xffff0000, v219
	v_pk_fma_f32 v[168:169], v[52:53], 0.5, v[168:169] op_sel_hi:[1,0,1]
	v_pk_fma_f32 v[170:171], v[54:55], 0.5, v[170:171] op_sel_hi:[1,0,1]
	v_pk_fma_f32 v[172:173], v[48:49], 0.5, v[172:173] op_sel_hi:[1,0,1]
	v_pk_fma_f32 v[174:175], v[50:51], 0.5, v[174:175] op_sel_hi:[1,0,1]
	v_pk_fma_f32 v[244:245], v[168:169], v[168:169], v[244:245]
	v_pk_fma_f32 v[244:245], v[170:171], v[170:171], v[244:245]
	v_pk_fma_f32 v[244:245], v[172:173], v[172:173], v[244:245]
	v_pk_fma_f32 v[244:245], v[174:175], v[174:175], v[244:245]
	v_cvt_pk_bf16_f32 v216, v168, v169
	v_cvt_pk_bf16_f32 v217, v170, v171
	v_cvt_pk_bf16_f32 v218, v172, v173
	v_cvt_pk_bf16_f32 v219, v174, v175
	global_store_dwordx4 v[164:165], v[216:219], off offset:256
	v_add_f32_e32 v246, v244, v245
	v_mov_b32_e32 v247, v246
	s_nop 1
	v_permlane32_swap_b32 v247, v246
	s_nop 1
	v_add_f32_e32 v246, v246, v247
	v_mov_b32_e32 v247, v246
	s_nop 1
	v_permlane16_swap_b32 v247, v246
	s_nop 1
	v_add_f32_e32 v246, v246, v247
	s_mov_b64 exec, s[46:47]
	global_atomic_add_f32 v[166:167], v246, off offset:512
	s_mov_b64 exec, -1
	s_mov_b64 vcc, 0x8000
	s_nop 0
	v_lshl_add_u64 v[164:165], v[164:165], 0, vcc
	s_waitcnt vmcnt(19)
	v_lshlrev_b32_e32 v168, 16, v220
	v_and_b32_e32 v169, 0xffff0000, v220
	v_lshlrev_b32_e32 v170, 16, v221
	v_and_b32_e32 v171, 0xffff0000, v221
	v_lshlrev_b32_e32 v172, 16, v222
	v_and_b32_e32 v173, 0xffff0000, v222
	v_lshlrev_b32_e32 v174, 16, v223
	v_and_b32_e32 v175, 0xffff0000, v223
	v_pk_fma_f32 v[168:169], v[44:45], 0.5, v[168:169] op_sel_hi:[1,0,1]
	v_pk_fma_f32 v[170:171], v[46:47], 0.5, v[170:171] op_sel_hi:[1,0,1]
	v_pk_fma_f32 v[172:173], v[40:41], 0.5, v[172:173] op_sel_hi:[1,0,1]
	v_pk_fma_f32 v[174:175], v[42:43], 0.5, v[174:175] op_sel_hi:[1,0,1]
	v_pk_mul_f32 v[244:245], v[168:169], v[168:169]
	v_pk_fma_f32 v[244:245], v[170:171], v[170:171], v[244:245]
	v_pk_fma_f32 v[244:245], v[172:173], v[172:173], v[244:245]
	v_pk_fma_f32 v[244:245], v[174:175], v[174:175], v[244:245]
	v_cvt_pk_bf16_f32 v220, v168, v169
	v_cvt_pk_bf16_f32 v221, v170, v171
	v_cvt_pk_bf16_f32 v222, v172, v173
	v_cvt_pk_bf16_f32 v223, v174, v175
	global_store_dwordx4 v[164:165], v[220:223], off
	v_lshlrev_b32_e32 v168, 16, v224
	v_and_b32_e32 v169, 0xffff0000, v224
	v_lshlrev_b32_e32 v170, 16, v225
	v_and_b32_e32 v171, 0xffff0000, v225
	v_lshlrev_b32_e32 v172, 16, v226
	v_and_b32_e32 v173, 0xffff0000, v226
	v_lshlrev_b32_e32 v174, 16, v227
	v_and_b32_e32 v175, 0xffff0000, v227
	v_pk_fma_f32 v[168:169], v[36:37], 0.5, v[168:169] op_sel_hi:[1,0,1]
	v_pk_fma_f32 v[170:171], v[38:39], 0.5, v[170:171] op_sel_hi:[1,0,1]
	v_pk_fma_f32 v[172:173], v[32:33], 0.5, v[172:173] op_sel_hi:[1,0,1]
	v_pk_fma_f32 v[174:175], v[34:35], 0.5, v[174:175] op_sel_hi:[1,0,1]
	v_pk_fma_f32 v[244:245], v[168:169], v[168:169], v[244:245]
	v_pk_fma_f32 v[244:245], v[170:171], v[170:171], v[244:245]
	v_pk_fma_f32 v[244:245], v[172:173], v[172:173], v[244:245]
	v_pk_fma_f32 v[244:245], v[174:175], v[174:175], v[244:245]
	v_cvt_pk_bf16_f32 v224, v168, v169
	v_cvt_pk_bf16_f32 v225, v170, v171
	v_cvt_pk_bf16_f32 v226, v172, v173
	v_cvt_pk_bf16_f32 v227, v174, v175
	global_store_dwordx4 v[164:165], v[224:227], off offset:256
	v_add_f32_e32 v246, v244, v245
	v_mov_b32_e32 v247, v246
	s_nop 1
	v_permlane32_swap_b32 v247, v246
	s_nop 1
	v_add_f32_e32 v246, v246, v247
	v_mov_b32_e32 v247, v246
	s_nop 1
	v_permlane16_swap_b32 v247, v246
	s_nop 1
	v_add_f32_e32 v246, v246, v247
	s_mov_b64 exec, s[46:47]
	global_atomic_add_f32 v[166:167], v246, off offset:576
	s_mov_b64 exec, -1
	s_mov_b64 vcc, 0x8000
	s_nop 0
	v_lshl_add_u64 v[164:165], v[164:165], 0, vcc
	s_waitcnt vmcnt(20)
	v_lshlrev_b32_e32 v168, 16, v228
	v_and_b32_e32 v169, 0xffff0000, v228
	v_lshlrev_b32_e32 v170, 16, v229
	v_and_b32_e32 v171, 0xffff0000, v229
	v_lshlrev_b32_e32 v172, 16, v230
	v_and_b32_e32 v173, 0xffff0000, v230
	v_lshlrev_b32_e32 v174, 16, v231
	v_and_b32_e32 v175, 0xffff0000, v231
	v_pk_fma_f32 v[168:169], v[28:29], 0.5, v[168:169] op_sel_hi:[1,0,1]
	v_pk_fma_f32 v[170:171], v[30:31], 0.5, v[170:171] op_sel_hi:[1,0,1]
	v_pk_fma_f32 v[172:173], v[24:25], 0.5, v[172:173] op_sel_hi:[1,0,1]
	v_pk_fma_f32 v[174:175], v[26:27], 0.5, v[174:175] op_sel_hi:[1,0,1]
	v_pk_mul_f32 v[244:245], v[168:169], v[168:169]
	v_pk_fma_f32 v[244:245], v[170:171], v[170:171], v[244:245]
	v_pk_fma_f32 v[244:245], v[172:173], v[172:173], v[244:245]
	v_pk_fma_f32 v[244:245], v[174:175], v[174:175], v[244:245]
	v_cvt_pk_bf16_f32 v228, v168, v169
	v_cvt_pk_bf16_f32 v229, v170, v171
	v_cvt_pk_bf16_f32 v230, v172, v173
	v_cvt_pk_bf16_f32 v231, v174, v175
	global_store_dwordx4 v[164:165], v[228:231], off
	v_lshlrev_b32_e32 v168, 16, v232
	v_and_b32_e32 v169, 0xffff0000, v232
	v_lshlrev_b32_e32 v170, 16, v233
	v_and_b32_e32 v171, 0xffff0000, v233
	v_lshlrev_b32_e32 v172, 16, v234
	v_and_b32_e32 v173, 0xffff0000, v234
	v_lshlrev_b32_e32 v174, 16, v235
	v_and_b32_e32 v175, 0xffff0000, v235
	v_pk_fma_f32 v[168:169], v[20:21], 0.5, v[168:169] op_sel_hi:[1,0,1]
	v_pk_fma_f32 v[170:171], v[22:23], 0.5, v[170:171] op_sel_hi:[1,0,1]
	v_pk_fma_f32 v[172:173], v[16:17], 0.5, v[172:173] op_sel_hi:[1,0,1]
	v_pk_fma_f32 v[174:175], v[18:19], 0.5, v[174:175] op_sel_hi:[1,0,1]
	v_pk_fma_f32 v[244:245], v[168:169], v[168:169], v[244:245]
	v_pk_fma_f32 v[244:245], v[170:171], v[170:171], v[244:245]
	v_pk_fma_f32 v[244:245], v[172:173], v[172:173], v[244:245]
	v_pk_fma_f32 v[244:245], v[174:175], v[174:175], v[244:245]
	v_cvt_pk_bf16_f32 v232, v168, v169
	v_cvt_pk_bf16_f32 v233, v170, v171
	v_cvt_pk_bf16_f32 v234, v172, v173
	v_cvt_pk_bf16_f32 v235, v174, v175
	global_store_dwordx4 v[164:165], v[232:235], off offset:256
	v_add_f32_e32 v246, v244, v245
	v_mov_b32_e32 v247, v246
	s_nop 1
	v_permlane32_swap_b32 v247, v246
	s_nop 1
	v_add_f32_e32 v246, v246, v247
	v_mov_b32_e32 v247, v246
	s_nop 1
	v_permlane16_swap_b32 v247, v246
	s_nop 1
	v_add_f32_e32 v246, v246, v247
	s_mov_b64 exec, s[46:47]
	global_atomic_add_f32 v[166:167], v246, off offset:640
	s_mov_b64 exec, -1
	s_mov_b64 vcc, 0x8000
	s_nop 0
	v_lshl_add_u64 v[164:165], v[164:165], 0, vcc
	s_waitcnt vmcnt(21)
	v_lshlrev_b32_e32 v168, 16, v236
	v_and_b32_e32 v169, 0xffff0000, v236
	v_lshlrev_b32_e32 v170, 16, v237
	v_and_b32_e32 v171, 0xffff0000, v237
	v_lshlrev_b32_e32 v172, 16, v238
	v_and_b32_e32 v173, 0xffff0000, v238
	v_lshlrev_b32_e32 v174, 16, v239
	v_and_b32_e32 v175, 0xffff0000, v239
	v_pk_fma_f32 v[168:169], v[12:13], 0.5, v[168:169] op_sel_hi:[1,0,1]
	v_pk_fma_f32 v[170:171], v[14:15], 0.5, v[170:171] op_sel_hi:[1,0,1]
	v_pk_fma_f32 v[172:173], v[8:9], 0.5, v[172:173] op_sel_hi:[1,0,1]
	v_pk_fma_f32 v[174:175], v[10:11], 0.5, v[174:175] op_sel_hi:[1,0,1]
	v_pk_mul_f32 v[244:245], v[168:169], v[168:169]
	v_pk_fma_f32 v[244:245], v[170:171], v[170:171], v[244:245]
	v_pk_fma_f32 v[244:245], v[172:173], v[172:173], v[244:245]
	v_pk_fma_f32 v[244:245], v[174:175], v[174:175], v[244:245]
	v_cvt_pk_bf16_f32 v236, v168, v169
	v_cvt_pk_bf16_f32 v237, v170, v171
	v_cvt_pk_bf16_f32 v238, v172, v173
	v_cvt_pk_bf16_f32 v239, v174, v175
	global_store_dwordx4 v[164:165], v[236:239], off
	v_lshlrev_b32_e32 v168, 16, v240
	v_and_b32_e32 v169, 0xffff0000, v240
	v_lshlrev_b32_e32 v170, 16, v241
	v_and_b32_e32 v171, 0xffff0000, v241
	v_lshlrev_b32_e32 v172, 16, v242
	v_and_b32_e32 v173, 0xffff0000, v242
	v_lshlrev_b32_e32 v174, 16, v243
	v_and_b32_e32 v175, 0xffff0000, v243
	v_pk_fma_f32 v[168:169], v[4:5], 0.5, v[168:169] op_sel_hi:[1,0,1]
	v_pk_fma_f32 v[170:171], v[6:7], 0.5, v[170:171] op_sel_hi:[1,0,1]
	v_pk_fma_f32 v[172:173], v[0:1], 0.5, v[172:173] op_sel_hi:[1,0,1]
	v_pk_fma_f32 v[174:175], v[2:3], 0.5, v[174:175] op_sel_hi:[1,0,1]
	v_pk_fma_f32 v[244:245], v[168:169], v[168:169], v[244:245]
	v_pk_fma_f32 v[244:245], v[170:171], v[170:171], v[244:245]
	v_pk_fma_f32 v[244:245], v[172:173], v[172:173], v[244:245]
	v_pk_fma_f32 v[244:245], v[174:175], v[174:175], v[244:245]
	v_cvt_pk_bf16_f32 v240, v168, v169
	v_cvt_pk_bf16_f32 v241, v170, v171
	v_cvt_pk_bf16_f32 v242, v172, v173
	v_cvt_pk_bf16_f32 v243, v174, v175
	global_store_dwordx4 v[164:165], v[240:243], off offset:256
	v_add_f32_e32 v246, v244, v245
	v_mov_b32_e32 v247, v246
	s_nop 1
	v_permlane32_swap_b32 v247, v246
	s_nop 1
	v_add_f32_e32 v246, v246, v247
	v_mov_b32_e32 v247, v246
	s_nop 1
	v_permlane16_swap_b32 v247, v246
	s_nop 1
	v_add_f32_e32 v246, v246, v247
	s_mov_b64 exec, s[46:47]
	global_atomic_add_f32 v[166:167], v246, off offset:704
	s_mov_b64 exec, -1
	s_mov_b64 s[42:43], exec
	s_branch .LBB0_659

.LBB0_878:
	s_andn2_b64 vcc, exec, s[0:1]
	s_cbranch_vccnz .LBB0_896
	v_ashrrev_i32_e32 v83, 2, v192
	v_and_b32_e32 v82, 15, v192
	v_and_b32_e32 v83, 0xffffffc0, v83
	v_add3_u32 v132, v82, s30, v83
	v_ashrrev_i32_e32 v133, 31, v132
	v_lshl_add_u64 v[82:83], v[132:133], 2, s[90:91]
	s_mov_b64 vcc, 0xe0000
	s_nop 0
	v_lshl_add_u64 v[82:83], v[82:83], 0, vcc
	global_load_dword v204, v[82:83], off
	global_load_dword v205, v[82:83], off offset:64
	global_load_dword v206, v[82:83], off offset:128
	global_load_dword v207, v[82:83], off offset:192
	global_load_dword v208, v[82:83], off offset:512
	global_load_dword v209, v[82:83], off offset:576
	global_load_dword v210, v[82:83], off offset:640
	global_load_dword v211, v[82:83], off offset:704
	v_bfe_u32 v134, v192, 4, 2
	v_lshrrev_b32_e32 v80, 1, v192
	v_and_b32_e32 v80, 0x60, v80
	v_add_u32_e32 v80, s6, v80
	v_lshl_add_u32 v80, v134, 3, v80
	v_lshlrev_b32_e32 v80, 1, v80
	v_lshlrev_b64 v[146:147], 11, v[132:133]
	v_lshl_add_u64 v[146:147], s[38:39], 0, v[146:147]
	v_lshl_add_u64 v[146:147], v[146:147], 0, v[80:81]
	v_mov_b32_e32 v248, v146
	v_mov_b32_e32 v249, v147
	global_load_dwordx4 v[148:151], v[248:249], off
	global_load_dwordx4 v[160:163], v[248:249], off offset:256
	s_mov_b64 vcc, 0x8000
	s_nop 0
	v_lshl_add_u64 v[248:249], v[248:249], 0, vcc
	global_load_dwordx4 v[176:179], v[248:249], off
	global_load_dwordx4 v[180:183], v[248:249], off offset:256
	s_mov_b64 vcc, 0x8000
	s_nop 0
	v_lshl_add_u64 v[248:249], v[248:249], 0, vcc
	global_load_dwordx4 v[184:187], v[248:249], off
	global_load_dwordx4 v[188:191], v[248:249], off offset:256
	s_mov_b64 vcc, 0x8000
	s_nop 0
	v_lshl_add_u64 v[248:249], v[248:249], 0, vcc
	global_load_dwordx4 v[212:215], v[248:249], off
	global_load_dwordx4 v[216:219], v[248:249], off offset:256
	s_mov_b64 vcc, 0x28000
	s_nop 0
	v_lshl_add_u64 v[248:249], v[248:249], 0, vcc
	global_load_dwordx4 v[220:223], v[248:249], off
	global_load_dwordx4 v[224:227], v[248:249], off offset:256
	s_mov_b64 vcc, 0x8000
	s_nop 0
	v_lshl_add_u64 v[248:249], v[248:249], 0, vcc
	global_load_dwordx4 v[228:231], v[248:249], off
	global_load_dwordx4 v[232:235], v[248:249], off offset:256
	s_mov_b64 vcc, 0x8000
	s_nop 0
	v_lshl_add_u64 v[248:249], v[248:249], 0, vcc
	global_load_dwordx4 v[236:239], v[248:249], off
	global_load_dwordx4 v[240:243], v[248:249], off offset:256
	s_mov_b64 vcc, 0x8000
	s_nop 0
	v_lshl_add_u64 v[248:249], v[248:249], 0, vcc
	global_load_dwordx4 v[164:167], v[248:249], off
	global_load_dwordx4 v[168:171], v[248:249], off offset:256
	v_readlane_b32 s10, v253, 47
	v_cmp_eq_u32_e64 s[40:41], 0, v134
	v_readlane_b32 s11, v253, 48
	s_nop 1
	v_lshl_add_u64 v[142:143], v[132:133], 2, s[10:11]
	s_waitcnt vmcnt(14)
	v_fmamk_f32 v250, v204, 0x3b000000, v194
	v_rsq_f32_e32 v250, v250
	s_nop 0
	v_mov_b32_e32 v80, v250
	v_lshlrev_b32_e32 v136, 16, v148
	v_and_b32_e32 v137, 0xffff0000, v148
	v_lshlrev_b32_e32 v138, 16, v149
	v_and_b32_e32 v139, 0xffff0000, v149
	v_lshlrev_b32_e32 v140, 16, v150
	v_and_b32_e32 v141, 0xffff0000, v150
	v_lshlrev_b32_e32 v144, 16, v151
	v_and_b32_e32 v145, 0xffff0000, v151
	v_pk_fma_f32 v[136:137], v[128:129], v[80:81], v[136:137] op_sel_hi:[1,0,1]
	v_pk_fma_f32 v[138:139], v[130:131], v[80:81], v[138:139] op_sel_hi:[1,0,1]
	v_pk_fma_f32 v[140:141], v[124:125], v[80:81], v[140:141] op_sel_hi:[1,0,1]
	v_pk_fma_f32 v[144:145], v[126:127], v[80:81], v[144:145] op_sel_hi:[1,0,1]
	v_pk_mul_f32 v[244:245], v[136:137], v[136:137]
	v_pk_fma_f32 v[244:245], v[138:139], v[138:139], v[244:245]
	v_pk_fma_f32 v[244:245], v[140:141], v[140:141], v[244:245]
	v_pk_fma_f32 v[244:245], v[144:145], v[144:145], v[244:245]
	v_cvt_pk_bf16_f32 v148, v136, v137
	v_cvt_pk_bf16_f32 v149, v138, v139
	v_cvt_pk_bf16_f32 v150, v140, v141
	v_cvt_pk_bf16_f32 v151, v144, v145
	global_store_dwordx4 v[146:147], v[148:151], off
	v_lshlrev_b32_e32 v136, 16, v160
	v_and_b32_e32 v137, 0xffff0000, v160
	v_lshlrev_b32_e32 v138, 16, v161
	v_and_b32_e32 v139, 0xffff0000, v161
	v_lshlrev_b32_e32 v140, 16, v162
	v_and_b32_e32 v141, 0xffff0000, v162
	v_lshlrev_b32_e32 v144, 16, v163
	v_and_b32_e32 v145, 0xffff0000, v163
	v_pk_fma_f32 v[136:137], v[120:121], v[80:81], v[136:137] op_sel_hi:[1,0,1]
	v_pk_fma_f32 v[138:139], v[122:123], v[80:81], v[138:139] op_sel_hi:[1,0,1]
	v_pk_fma_f32 v[140:141], v[116:117], v[80:81], v[140:141] op_sel_hi:[1,0,1]
	v_pk_fma_f32 v[144:145], v[118:119], v[80:81], v[144:145] op_sel_hi:[1,0,1]
	v_pk_fma_f32 v[244:245], v[136:137], v[136:137], v[244:245]
	v_pk_fma_f32 v[244:245], v[138:139], v[138:139], v[244:245]
	v_pk_fma_f32 v[244:245], v[140:141], v[140:141], v[244:245]
	v_pk_fma_f32 v[244:245], v[144:145], v[144:145], v[244:245]
	v_cvt_pk_bf16_f32 v160, v136, v137
	v_cvt_pk_bf16_f32 v161, v138, v139
	v_cvt_pk_bf16_f32 v162, v140, v141
	v_cvt_pk_bf16_f32 v163, v144, v145
	global_store_dwordx4 v[146:147], v[160:163], off offset:256
	v_add_f32_e32 v246, v244, v245
	v_mov_b32_e32 v247, v246
	s_nop 1
	v_permlane32_swap_b32 v247, v246
	s_nop 1
	v_add_f32_e32 v246, v246, v247
	v_mov_b32_e32 v247, v246
	s_nop 1
	v_permlane16_swap_b32 v247, v246
	s_nop 1
	v_add_f32_e32 v246, v246, v247
	s_mov_b64 exec, s[40:41]
	global_atomic_add_f32 v[142:143], v246, off
	s_mov_b64 exec, -1
	s_mov_b64 vcc, 0x8000
	s_nop 0
	v_lshl_add_u64 v[146:147], v[146:147], 0, vcc
	s_waitcnt vmcnt(15)
	v_fmamk_f32 v250, v205, 0x3b000000, v194
	v_rsq_f32_e32 v250, v250
	s_nop 0
	v_mov_b32_e32 v80, v250
	v_lshlrev_b32_e32 v136, 16, v176
	v_and_b32_e32 v137, 0xffff0000, v176
	v_lshlrev_b32_e32 v138, 16, v177
	v_and_b32_e32 v139, 0xffff0000, v177
	v_lshlrev_b32_e32 v140, 16, v178
	v_and_b32_e32 v141, 0xffff0000, v178
	v_lshlrev_b32_e32 v144, 16, v179
	v_and_b32_e32 v145, 0xffff0000, v179
	v_pk_fma_f32 v[136:137], v[112:113], v[80:81], v[136:137] op_sel_hi:[1,0,1]
	v_pk_fma_f32 v[138:139], v[114:115], v[80:81], v[138:139] op_sel_hi:[1,0,1]
	v_pk_fma_f32 v[140:141], v[108:109], v[80:81], v[140:141] op_sel_hi:[1,0,1]
	v_pk_fma_f32 v[144:145], v[110:111], v[80:81], v[144:145] op_sel_hi:[1,0,1]
	v_pk_mul_f32 v[244:245], v[136:137], v[136:137]
	v_pk_fma_f32 v[244:245], v[138:139], v[138:139], v[244:245]
	v_pk_fma_f32 v[244:245], v[140:141], v[140:141], v[244:245]
	v_pk_fma_f32 v[244:245], v[144:145], v[144:145], v[244:245]
	v_cvt_pk_bf16_f32 v176, v136, v137
	v_cvt_pk_bf16_f32 v177, v138, v139
	v_cvt_pk_bf16_f32 v178, v140, v141
	v_cvt_pk_bf16_f32 v179, v144, v145
	global_store_dwordx4 v[146:147], v[176:179], off
	v_lshlrev_b32_e32 v136, 16, v180
	v_and_b32_e32 v137, 0xffff0000, v180
	v_lshlrev_b32_e32 v138, 16, v181
	v_and_b32_e32 v139, 0xffff0000, v181
	v_lshlrev_b32_e32 v140, 16, v182
	v_and_b32_e32 v141, 0xffff0000, v182
	v_lshlrev_b32_e32 v144, 16, v183
	v_and_b32_e32 v145, 0xffff0000, v183
	v_pk_fma_f32 v[136:137], v[104:105], v[80:81], v[136:137] op_sel_hi:[1,0,1]
	v_pk_fma_f32 v[138:139], v[106:107], v[80:81], v[138:139] op_sel_hi:[1,0,1]
	v_pk_fma_f32 v[140:141], v[100:101], v[80:81], v[140:141] op_sel_hi:[1,0,1]
	v_pk_fma_f32 v[144:145], v[102:103], v[80:81], v[144:145] op_sel_hi:[1,0,1]
	v_pk_fma_f32 v[244:245], v[136:137], v[136:137], v[244:245]
	v_pk_fma_f32 v[244:245], v[138:139], v[138:139], v[244:245]
	v_pk_fma_f32 v[244:245], v[140:141], v[140:141], v[244:245]
	v_pk_fma_f32 v[244:245], v[144:145], v[144:145], v[244:245]
	v_cvt_pk_bf16_f32 v180, v136, v137
	v_cvt_pk_bf16_f32 v181, v138, v139
	v_cvt_pk_bf16_f32 v182, v140, v141
	v_cvt_pk_bf16_f32 v183, v144, v145
	global_store_dwordx4 v[146:147], v[180:183], off offset:256
	v_add_f32_e32 v246, v244, v245
	v_mov_b32_e32 v247, v246
	s_nop 1
	v_permlane32_swap_b32 v247, v246
	s_nop 1
	v_add_f32_e32 v246, v246, v247
	v_mov_b32_e32 v247, v246
	s_nop 1
	v_permlane16_swap_b32 v247, v246
	s_nop 1
	v_add_f32_e32 v246, v246, v247
	s_mov_b64 exec, s[40:41]
	global_atomic_add_f32 v[142:143], v246, off offset:64
	s_mov_b64 exec, -1
	s_mov_b64 vcc, 0x8000
	s_nop 0
	v_lshl_add_u64 v[146:147], v[146:147], 0, vcc
	s_waitcnt vmcnt(16)
	v_fmamk_f32 v250, v206, 0x3b000000, v194
	v_rsq_f32_e32 v250, v250
	s_nop 0
	v_mov_b32_e32 v80, v250
	v_lshlrev_b32_e32 v136, 16, v184
	v_and_b32_e32 v137, 0xffff0000, v184
	v_lshlrev_b32_e32 v138, 16, v185
	v_and_b32_e32 v139, 0xffff0000, v185
	v_lshlrev_b32_e32 v140, 16, v186
	v_and_b32_e32 v141, 0xffff0000, v186
	v_lshlrev_b32_e32 v144, 16, v187
	v_and_b32_e32 v145, 0xffff0000, v187
	v_pk_fma_f32 v[136:137], v[96:97], v[80:81], v[136:137] op_sel_hi:[1,0,1]
	v_pk_fma_f32 v[138:139], v[98:99], v[80:81], v[138:139] op_sel_hi:[1,0,1]
	v_pk_fma_f32 v[140:141], v[92:93], v[80:81], v[140:141] op_sel_hi:[1,0,1]
	v_pk_fma_f32 v[144:145], v[94:95], v[80:81], v[144:145] op_sel_hi:[1,0,1]
	v_pk_mul_f32 v[244:245], v[136:137], v[136:137]
	v_pk_fma_f32 v[244:245], v[138:139], v[138:139], v[244:245]
	v_pk_fma_f32 v[244:245], v[140:141], v[140:141], v[244:245]
	v_pk_fma_f32 v[244:245], v[144:145], v[144:145], v[244:245]
	v_cvt_pk_bf16_f32 v184, v136, v137
	v_cvt_pk_bf16_f32 v185, v138, v139
	v_cvt_pk_bf16_f32 v186, v140, v141
	v_cvt_pk_bf16_f32 v187, v144, v145
	global_store_dwordx4 v[146:147], v[184:187], off
	v_lshlrev_b32_e32 v136, 16, v188
	v_and_b32_e32 v137, 0xffff0000, v188
	v_lshlrev_b32_e32 v138, 16, v189
	v_and_b32_e32 v139, 0xffff0000, v189
	v_lshlrev_b32_e32 v140, 16, v190
	v_and_b32_e32 v141, 0xffff0000, v190
	v_lshlrev_b32_e32 v144, 16, v191
	v_and_b32_e32 v145, 0xffff0000, v191
	v_pk_fma_f32 v[136:137], v[88:89], v[80:81], v[136:137] op_sel_hi:[1,0,1]
	v_pk_fma_f32 v[138:139], v[90:91], v[80:81], v[138:139] op_sel_hi:[1,0,1]
	v_pk_fma_f32 v[140:141], v[84:85], v[80:81], v[140:141] op_sel_hi:[1,0,1]
	v_pk_fma_f32 v[144:145], v[86:87], v[80:81], v[144:145] op_sel_hi:[1,0,1]
	v_pk_fma_f32 v[244:245], v[136:137], v[136:137], v[244:245]
	v_pk_fma_f32 v[244:245], v[138:139], v[138:139], v[244:245]
	v_pk_fma_f32 v[244:245], v[140:141], v[140:141], v[244:245]
	v_pk_fma_f32 v[244:245], v[144:145], v[144:145], v[244:245]
	v_cvt_pk_bf16_f32 v188, v136, v137
	v_cvt_pk_bf16_f32 v189, v138, v139
	v_cvt_pk_bf16_f32 v190, v140, v141
	v_cvt_pk_bf16_f32 v191, v144, v145
	global_store_dwordx4 v[146:147], v[188:191], off offset:256
	v_add_f32_e32 v246, v244, v245
	v_mov_b32_e32 v247, v246
	s_nop 1
	v_permlane32_swap_b32 v247, v246
	s_nop 1
	v_add_f32_e32 v246, v246, v247
	v_mov_b32_e32 v247, v246
	s_nop 1
	v_permlane16_swap_b32 v247, v246
	s_nop 1
	v_add_f32_e32 v246, v246, v247
	s_mov_b64 exec, s[40:41]
	global_atomic_add_f32 v[142:143], v246, off offset:128
	s_mov_b64 exec, -1
	s_mov_b64 vcc, 0x8000
	s_nop 0
	v_lshl_add_u64 v[146:147], v[146:147], 0, vcc
	s_waitcnt vmcnt(17)
	v_fmamk_f32 v250, v207, 0x3b000000, v194
	v_rsq_f32_e32 v250, v250
	s_nop 0
	v_mov_b32_e32 v80, v250
	v_lshlrev_b32_e32 v136, 16, v212
	v_and_b32_e32 v137, 0xffff0000, v212
	v_lshlrev_b32_e32 v138, 16, v213
	v_and_b32_e32 v139, 0xffff0000, v213
	v_lshlrev_b32_e32 v140, 16, v214
	v_and_b32_e32 v141, 0xffff0000, v214
	v_lshlrev_b32_e32 v144, 16, v215
	v_and_b32_e32 v145, 0xffff0000, v215
	v_pk_fma_f32 v[136:137], v[76:77], v[80:81], v[136:137] op_sel_hi:[1,0,1]
	v_pk_fma_f32 v[138:139], v[78:79], v[80:81], v[138:139] op_sel_hi:[1,0,1]
	v_pk_fma_f32 v[140:141], v[72:73], v[80:81], v[140:141] op_sel_hi:[1,0,1]
	v_pk_fma_f32 v[144:145], v[74:75], v[80:81], v[144:145] op_sel_hi:[1,0,1]
	v_pk_mul_f32 v[244:245], v[136:137], v[136:137]
	v_pk_fma_f32 v[244:245], v[138:139], v[138:139], v[244:245]
	v_pk_fma_f32 v[244:245], v[140:141], v[140:141], v[244:245]
	v_pk_fma_f32 v[244:245], v[144:145], v[144:145], v[244:245]
	v_cvt_pk_bf16_f32 v212, v136, v137
	v_cvt_pk_bf16_f32 v213, v138, v139
	v_cvt_pk_bf16_f32 v214, v140, v141
	v_cvt_pk_bf16_f32 v215, v144, v145
	global_store_dwordx4 v[146:147], v[212:215], off
	v_lshlrev_b32_e32 v136, 16, v216
	v_and_b32_e32 v137, 0xffff0000, v216
	v_lshlrev_b32_e32 v138, 16, v217
	v_and_b32_e32 v139, 0xffff0000, v217
	v_lshlrev_b32_e32 v140, 16, v218
	v_and_b32_e32 v141, 0xffff0000, v218
	v_lshlrev_b32_e32 v144, 16, v219
	v_and_b32_e32 v145, 0xffff0000, v219
	v_pk_fma_f32 v[136:137], v[68:69], v[80:81], v[136:137] op_sel_hi:[1,0,1]
	v_pk_fma_f32 v[138:139], v[70:71], v[80:81], v[138:139] op_sel_hi:[1,0,1]
	v_pk_fma_f32 v[140:141], v[64:65], v[80:81], v[140:141] op_sel_hi:[1,0,1]
	v_pk_fma_f32 v[144:145], v[66:67], v[80:81], v[144:145] op_sel_hi:[1,0,1]
	v_pk_fma_f32 v[244:245], v[136:137], v[136:137], v[244:245]
	v_pk_fma_f32 v[244:245], v[138:139], v[138:139], v[244:245]
	v_pk_fma_f32 v[244:245], v[140:141], v[140:141], v[244:245]
	v_pk_fma_f32 v[244:245], v[144:145], v[144:145], v[244:245]
	v_cvt_pk_bf16_f32 v216, v136, v137
	v_cvt_pk_bf16_f32 v217, v138, v139
	v_cvt_pk_bf16_f32 v218, v140, v141
	v_cvt_pk_bf16_f32 v219, v144, v145
	global_store_dwordx4 v[146:147], v[216:219], off offset:256
	v_add_f32_e32 v246, v244, v245
	v_mov_b32_e32 v247, v246
	s_nop 1
	v_permlane32_swap_b32 v247, v246
	s_nop 1
	v_add_f32_e32 v246, v246, v247
	v_mov_b32_e32 v247, v246
	s_nop 1
	v_permlane16_swap_b32 v247, v246
	s_nop 1
	v_add_f32_e32 v246, v246, v247
	s_mov_b64 exec, s[40:41]
	global_atomic_add_f32 v[142:143], v246, off offset:192
	s_mov_b64 exec, -1
	s_mov_b64 vcc, 0x28000
	s_nop 0
	v_lshl_add_u64 v[146:147], v[146:147], 0, vcc
	s_waitcnt vmcnt(18)
	v_fmamk_f32 v250, v208, 0x3b000000, v194
	v_rsq_f32_e32 v250, v250
	s_nop 0
	v_mov_b32_e32 v80, v250
	v_lshlrev_b32_e32 v136, 16, v220
	v_and_b32_e32 v137, 0xffff0000, v220
	v_lshlrev_b32_e32 v138, 16, v221
	v_and_b32_e32 v139, 0xffff0000, v221
	v_lshlrev_b32_e32 v140, 16, v222
	v_and_b32_e32 v141, 0xffff0000, v222
	v_lshlrev_b32_e32 v144, 16, v223
	v_and_b32_e32 v145, 0xffff0000, v223
	v_pk_fma_f32 v[136:137], v[60:61], v[80:81], v[136:137] op_sel_hi:[1,0,1]
	v_pk_fma_f32 v[138:139], v[62:63], v[80:81], v[138:139] op_sel_hi:[1,0,1]
	v_pk_fma_f32 v[140:141], v[56:57], v[80:81], v[140:141] op_sel_hi:[1,0,1]
	v_pk_fma_f32 v[144:145], v[58:59], v[80:81], v[144:145] op_sel_hi:[1,0,1]
	v_pk_mul_f32 v[244:245], v[136:137], v[136:137]
	v_pk_fma_f32 v[244:245], v[138:139], v[138:139], v[244:245]
	v_pk_fma_f32 v[244:245], v[140:141], v[140:141], v[244:245]
	v_pk_fma_f32 v[244:245], v[144:145], v[144:145], v[244:245]
	v_cvt_pk_bf16_f32 v220, v136, v137
	v_cvt_pk_bf16_f32 v221, v138, v139
	v_cvt_pk_bf16_f32 v222, v140, v141
	v_cvt_pk_bf16_f32 v223, v144, v145
	global_store_dwordx4 v[146:147], v[220:223], off
	v_lshlrev_b32_e32 v136, 16, v224
	v_and_b32_e32 v137, 0xffff0000, v224
	v_lshlrev_b32_e32 v138, 16, v225
	v_and_b32_e32 v139, 0xffff0000, v225
	v_lshlrev_b32_e32 v140, 16, v226
	v_and_b32_e32 v141, 0xffff0000, v226
	v_lshlrev_b32_e32 v144, 16, v227
	v_and_b32_e32 v145, 0xffff0000, v227
	v_pk_fma_f32 v[136:137], v[52:53], v[80:81], v[136:137] op_sel_hi:[1,0,1]
	v_pk_fma_f32 v[138:139], v[54:55], v[80:81], v[138:139] op_sel_hi:[1,0,1]
	v_pk_fma_f32 v[140:141], v[48:49], v[80:81], v[140:141] op_sel_hi:[1,0,1]
	v_pk_fma_f32 v[144:145], v[50:51], v[80:81], v[144:145] op_sel_hi:[1,0,1]
	v_pk_fma_f32 v[244:245], v[136:137], v[136:137], v[244:245]
	v_pk_fma_f32 v[244:245], v[138:139], v[138:139], v[244:245]
	v_pk_fma_f32 v[244:245], v[140:141], v[140:141], v[244:245]
	v_pk_fma_f32 v[244:245], v[144:145], v[144:145], v[244:245]
	v_cvt_pk_bf16_f32 v224, v136, v137
	v_cvt_pk_bf16_f32 v225, v138, v139
	v_cvt_pk_bf16_f32 v226, v140, v141
	v_cvt_pk_bf16_f32 v227, v144, v145
	global_store_dwordx4 v[146:147], v[224:227], off offset:256
	v_add_f32_e32 v246, v244, v245
	v_mov_b32_e32 v247, v246
	s_nop 1
	v_permlane32_swap_b32 v247, v246
	s_nop 1
	v_add_f32_e32 v246, v246, v247
	v_mov_b32_e32 v247, v246
	s_nop 1
	v_permlane16_swap_b32 v247, v246
	s_nop 1
	v_add_f32_e32 v246, v246, v247
	s_mov_b64 exec, s[40:41]
	global_atomic_add_f32 v[142:143], v246, off offset:512
	s_mov_b64 exec, -1
	s_mov_b64 vcc, 0x8000
	s_nop 0
	v_lshl_add_u64 v[146:147], v[146:147], 0, vcc
	s_waitcnt vmcnt(19)
	v_fmamk_f32 v250, v209, 0x3b000000, v194
	v_rsq_f32_e32 v250, v250
	s_nop 0
	v_mov_b32_e32 v80, v250
	v_lshlrev_b32_e32 v136, 16, v228
	v_and_b32_e32 v137, 0xffff0000, v228
	v_lshlrev_b32_e32 v138, 16, v229
	v_and_b32_e32 v139, 0xffff0000, v229
	v_lshlrev_b32_e32 v140, 16, v230
	v_and_b32_e32 v141, 0xffff0000, v230
	v_lshlrev_b32_e32 v144, 16, v231
	v_and_b32_e32 v145, 0xffff0000, v231
	v_pk_fma_f32 v[136:137], v[44:45], v[80:81], v[136:137] op_sel_hi:[1,0,1]
	v_pk_fma_f32 v[138:139], v[46:47], v[80:81], v[138:139] op_sel_hi:[1,0,1]
	v_pk_fma_f32 v[140:141], v[40:41], v[80:81], v[140:141] op_sel_hi:[1,0,1]
	v_pk_fma_f32 v[144:145], v[42:43], v[80:81], v[144:145] op_sel_hi:[1,0,1]
	v_pk_mul_f32 v[244:245], v[136:137], v[136:137]
	v_pk_fma_f32 v[244:245], v[138:139], v[138:139], v[244:245]
	v_pk_fma_f32 v[244:245], v[140:141], v[140:141], v[244:245]
	v_pk_fma_f32 v[244:245], v[144:145], v[144:145], v[244:245]
	v_cvt_pk_bf16_f32 v228, v136, v137
	v_cvt_pk_bf16_f32 v229, v138, v139
	v_cvt_pk_bf16_f32 v230, v140, v141
	v_cvt_pk_bf16_f32 v231, v144, v145
	global_store_dwordx4 v[146:147], v[228:231], off
	v_lshlrev_b32_e32 v136, 16, v232
	v_and_b32_e32 v137, 0xffff0000, v232
	v_lshlrev_b32_e32 v138, 16, v233
	v_and_b32_e32 v139, 0xffff0000, v233
	v_lshlrev_b32_e32 v140, 16, v234
	v_and_b32_e32 v141, 0xffff0000, v234
	v_lshlrev_b32_e32 v144, 16, v235
	v_and_b32_e32 v145, 0xffff0000, v235
	v_pk_fma_f32 v[136:137], v[36:37], v[80:81], v[136:137] op_sel_hi:[1,0,1]
	v_pk_fma_f32 v[138:139], v[38:39], v[80:81], v[138:139] op_sel_hi:[1,0,1]
	v_pk_fma_f32 v[140:141], v[32:33], v[80:81], v[140:141] op_sel_hi:[1,0,1]
	v_pk_fma_f32 v[144:145], v[34:35], v[80:81], v[144:145] op_sel_hi:[1,0,1]
	v_pk_fma_f32 v[244:245], v[136:137], v[136:137], v[244:245]
	v_pk_fma_f32 v[244:245], v[138:139], v[138:139], v[244:245]
	v_pk_fma_f32 v[244:245], v[140:141], v[140:141], v[244:245]
	v_pk_fma_f32 v[244:245], v[144:145], v[144:145], v[244:245]
	v_cvt_pk_bf16_f32 v232, v136, v137
	v_cvt_pk_bf16_f32 v233, v138, v139
	v_cvt_pk_bf16_f32 v234, v140, v141
	v_cvt_pk_bf16_f32 v235, v144, v145
	global_store_dwordx4 v[146:147], v[232:235], off offset:256
	v_add_f32_e32 v246, v244, v245
	v_mov_b32_e32 v247, v246
	s_nop 1
	v_permlane32_swap_b32 v247, v246
	s_nop 1
	v_add_f32_e32 v246, v246, v247
	v_mov_b32_e32 v247, v246
	s_nop 1
	v_permlane16_swap_b32 v247, v246
	s_nop 1
	v_add_f32_e32 v246, v246, v247
	s_mov_b64 exec, s[40:41]
	global_atomic_add_f32 v[142:143], v246, off offset:576
	s_mov_b64 exec, -1
	s_mov_b64 vcc, 0x8000
	s_nop 0
	v_lshl_add_u64 v[146:147], v[146:147], 0, vcc
	s_waitcnt vmcnt(20)
	v_fmamk_f32 v250, v210, 0x3b000000, v194
	v_rsq_f32_e32 v250, v250
	s_nop 0
	v_mov_b32_e32 v80, v250
	v_lshlrev_b32_e32 v136, 16, v236
	v_and_b32_e32 v137, 0xffff0000, v236
	v_lshlrev_b32_e32 v138, 16, v237
	v_and_b32_e32 v139, 0xffff0000, v237
	v_lshlrev_b32_e32 v140, 16, v238
	v_and_b32_e32 v141, 0xffff0000, v238
	v_lshlrev_b32_e32 v144, 16, v239
	v_and_b32_e32 v145, 0xffff0000, v239
	v_pk_fma_f32 v[136:137], v[28:29], v[80:81], v[136:137] op_sel_hi:[1,0,1]
	v_pk_fma_f32 v[138:139], v[30:31], v[80:81], v[138:139] op_sel_hi:[1,0,1]
	v_pk_fma_f32 v[140:141], v[24:25], v[80:81], v[140:141] op_sel_hi:[1,0,1]
	v_pk_fma_f32 v[144:145], v[26:27], v[80:81], v[144:145] op_sel_hi:[1,0,1]
	v_pk_mul_f32 v[244:245], v[136:137], v[136:137]
	v_pk_fma_f32 v[244:245], v[138:139], v[138:139], v[244:245]
	v_pk_fma_f32 v[244:245], v[140:141], v[140:141], v[244:245]
	v_pk_fma_f32 v[244:245], v[144:145], v[144:145], v[244:245]
	v_cvt_pk_bf16_f32 v236, v136, v137
	v_cvt_pk_bf16_f32 v237, v138, v139
	v_cvt_pk_bf16_f32 v238, v140, v141
	v_cvt_pk_bf16_f32 v239, v144, v145
	global_store_dwordx4 v[146:147], v[236:239], off
	v_lshlrev_b32_e32 v136, 16, v240
	v_and_b32_e32 v137, 0xffff0000, v240
	v_lshlrev_b32_e32 v138, 16, v241
	v_and_b32_e32 v139, 0xffff0000, v241
	v_lshlrev_b32_e32 v140, 16, v242
	v_and_b32_e32 v141, 0xffff0000, v242
	v_lshlrev_b32_e32 v144, 16, v243
	v_and_b32_e32 v145, 0xffff0000, v243
	v_pk_fma_f32 v[136:137], v[20:21], v[80:81], v[136:137] op_sel_hi:[1,0,1]
	v_pk_fma_f32 v[138:139], v[22:23], v[80:81], v[138:139] op_sel_hi:[1,0,1]
	v_pk_fma_f32 v[140:141], v[16:17], v[80:81], v[140:141] op_sel_hi:[1,0,1]
	v_pk_fma_f32 v[144:145], v[18:19], v[80:81], v[144:145] op_sel_hi:[1,0,1]
	v_pk_fma_f32 v[244:245], v[136:137], v[136:137], v[244:245]
	v_pk_fma_f32 v[244:245], v[138:139], v[138:139], v[244:245]
	v_pk_fma_f32 v[244:245], v[140:141], v[140:141], v[244:245]
	v_pk_fma_f32 v[244:245], v[144:145], v[144:145], v[244:245]
	v_cvt_pk_bf16_f32 v240, v136, v137
	v_cvt_pk_bf16_f32 v241, v138, v139
	v_cvt_pk_bf16_f32 v242, v140, v141
	v_cvt_pk_bf16_f32 v243, v144, v145
	global_store_dwordx4 v[146:147], v[240:243], off offset:256
	v_add_f32_e32 v246, v244, v245
	v_mov_b32_e32 v247, v246
	s_nop 1
	v_permlane32_swap_b32 v247, v246
	s_nop 1
	v_add_f32_e32 v246, v246, v247
	v_mov_b32_e32 v247, v246
	s_nop 1
	v_permlane16_swap_b32 v247, v246
	s_nop 1
	v_add_f32_e32 v246, v246, v247
	s_mov_b64 exec, s[40:41]
	global_atomic_add_f32 v[142:143], v246, off offset:640
	s_mov_b64 exec, -1
	s_mov_b64 vcc, 0x8000
	s_nop 0
	v_lshl_add_u64 v[146:147], v[146:147], 0, vcc
	s_waitcnt vmcnt(21)
	v_fmamk_f32 v250, v211, 0x3b000000, v194
	v_rsq_f32_e32 v250, v250
	s_nop 0
	v_mov_b32_e32 v80, v250
	v_lshlrev_b32_e32 v136, 16, v164
	v_and_b32_e32 v137, 0xffff0000, v164
	v_lshlrev_b32_e32 v138, 16, v165
	v_and_b32_e32 v139, 0xffff0000, v165
	v_lshlrev_b32_e32 v140, 16, v166
	v_and_b32_e32 v141, 0xffff0000, v166
	v_lshlrev_b32_e32 v144, 16, v167
	v_and_b32_e32 v145, 0xffff0000, v167
	v_pk_fma_f32 v[136:137], v[12:13], v[80:81], v[136:137] op_sel_hi:[1,0,1]
	v_pk_fma_f32 v[138:139], v[14:15], v[80:81], v[138:139] op_sel_hi:[1,0,1]
	v_pk_fma_f32 v[140:141], v[8:9], v[80:81], v[140:141] op_sel_hi:[1,0,1]
	v_pk_fma_f32 v[144:145], v[10:11], v[80:81], v[144:145] op_sel_hi:[1,0,1]
	v_pk_mul_f32 v[244:245], v[136:137], v[136:137]
	v_pk_fma_f32 v[244:245], v[138:139], v[138:139], v[244:245]
	v_pk_fma_f32 v[244:245], v[140:141], v[140:141], v[244:245]
	v_pk_fma_f32 v[244:245], v[144:145], v[144:145], v[244:245]
	v_cvt_pk_bf16_f32 v164, v136, v137
	v_cvt_pk_bf16_f32 v165, v138, v139
	v_cvt_pk_bf16_f32 v166, v140, v141
	v_cvt_pk_bf16_f32 v167, v144, v145
	global_store_dwordx4 v[146:147], v[164:167], off
	v_lshlrev_b32_e32 v136, 16, v168
	v_and_b32_e32 v137, 0xffff0000, v168
	v_lshlrev_b32_e32 v138, 16, v169
	v_and_b32_e32 v139, 0xffff0000, v169
	v_lshlrev_b32_e32 v140, 16, v170
	v_and_b32_e32 v141, 0xffff0000, v170
	v_lshlrev_b32_e32 v144, 16, v171
	v_and_b32_e32 v145, 0xffff0000, v171
	v_pk_fma_f32 v[136:137], v[4:5], v[80:81], v[136:137] op_sel_hi:[1,0,1]
	v_pk_fma_f32 v[138:139], v[6:7], v[80:81], v[138:139] op_sel_hi:[1,0,1]
	v_pk_fma_f32 v[140:141], v[0:1], v[80:81], v[140:141] op_sel_hi:[1,0,1]
	v_pk_fma_f32 v[144:145], v[2:3], v[80:81], v[144:145] op_sel_hi:[1,0,1]
	v_pk_fma_f32 v[244:245], v[136:137], v[136:137], v[244:245]
	v_pk_fma_f32 v[244:245], v[138:139], v[138:139], v[244:245]
	v_pk_fma_f32 v[244:245], v[140:141], v[140:141], v[244:245]
	v_pk_fma_f32 v[244:245], v[144:145], v[144:145], v[244:245]
	v_cvt_pk_bf16_f32 v168, v136, v137
	v_cvt_pk_bf16_f32 v169, v138, v139
	v_cvt_pk_bf16_f32 v170, v140, v141
	v_cvt_pk_bf16_f32 v171, v144, v145
	global_store_dwordx4 v[146:147], v[168:171], off offset:256
	v_add_f32_e32 v246, v244, v245
	v_mov_b32_e32 v247, v246
	s_nop 1
	v_permlane32_swap_b32 v247, v246
	s_nop 1
	v_add_f32_e32 v246, v246, v247
	v_mov_b32_e32 v247, v246
	s_nop 1
	v_permlane16_swap_b32 v247, v246
	s_nop 1
	v_add_f32_e32 v246, v246, v247
	s_mov_b64 exec, s[40:41]
	global_atomic_add_f32 v[142:143], v246, off offset:704
	s_mov_b64 exec, -1
